# static priority: lead wave group (wr==0) runs the tile epilogue at s_setprio 3 so it reaches the next tile's first load segment earlier; reset to 0 at phase exit
# baseline (speedup 1.0000x reference)
; #define PG8_STAGE(bufoff, gbase, voff) do { _Pragma("unroll") for (int _i = 0; _i < 2; ++_i) \
;         __builtin_amdgcn_global_load_lds((const __attribute__((address_space(1))) unsigned*)((const char*)(gbase) + (voff)[_i]), (LAS unsigned*)(lds + (bufoff) + ldsw + _i * 8192), 16, 0, 0); } while (0)
; #define PG8_LDA(dst, b, h) do { _Pragma("unroll") for (int m = 0; m < 4; ++m) _Pragma("unroll") for (int k = 0; k < 2; ++k) dst[m][k] = *(const LAS bf16x8*)(lds + PG8_SA(b, h) + aoff + m * 2048 + k * 1024); } while (0)
; #define PG8_LDB(dst, b, h) do { _Pragma("unroll") for (int n = 0; n < 2; ++n) _Pragma("unroll") for (int k = 0; k < 2; ++k) dst[n][k] = *(const LAS bf16x8*)(lds + PG8_SB(b, h) + boff + n * 2048 + k * 1024); } while (0)
; #define PG8_MMA(ai, bj, At, Bt) do { __builtin_amdgcn_s_setprio(1); _Pragma("unroll") for (int m = 0; m < 4; ++m) _Pragma("unroll") for (int n = 0; n < 2; ++n) _Pragma("unroll") for (int k = 0; k < 2; ++k) \
;         acc[ai][bj][m][n] = __builtin_amdgcn_mfma_f32_16x16x32_bf16(Bt[n][k], At[m][k], acc[ai][bj][m][n], 0, 0, 0); __builtin_amdgcn_s_setprio(0); } while (0)
; #define PG8_WAIT_V(n) asm volatile("s_waitcnt vmcnt(" #n ")" ::: "memory")
; #define PG8_WAIT_L(n) asm volatile("s_waitcnt lgkmcnt(" #n ")" ::: "memory")
; #define PG8_BAR __builtin_amdgcn_s_barrier()
; #define PG8_SCHED __builtin_amdgcn_sched_barrier(0)
; template <class Epi, class SchedT, bool ALIGN_EPI, bool SP2>
; __device__ __forceinline__ void gemm_phase(LAS unsigned char* lds, const int ldk, const int nt, const SchedT& S, const Epi& E) {
;     ...
;             const bool last = (t == nt - 2);
;             const char* a1 = cA + (size_t)(t + 1) * kstep;
;             const char* a2 = last ? nA : cA + (size_t)(t + 2) * kstep; const char* b2 = last ? nB : cB + (size_t)(t + 2) * kstep;
;             const char* a3 = a2 + kstep; const char* b3 = b2 + kstep;
;             if constexpr (SP2) {
;             PG8_LDB(B0, 0, 0); PG8_LDB(B1, 0, 1); PG8_SCHED; PG8_LDA(At, 0, 0); PG8_STAGE(PG8_SA(1, 1), a1 + hstep, voffA);
;             PG8_WAIT_V(8); PG8_WAIT_L(0); PG8_BAR; PG8_MMA(0, 0, At, B0); PG8_MMA(0, 1, At, B1); PG8_BAR; PG8_SCHED;
;             PG8_LDA(At, 0, 1); PG8_STAGE(PG8_SB(0, 0), b2, voffB); PG8_STAGE(PG8_SB(0, 1), b2 + hstepB, voffB); PG8_STAGE(PG8_SA(0, 0), a2, voffA);
.LBB0_123:
	s_add_u32 s12, s0, 0xfff80080
	s_addc_u32 s13, s1, -1
	s_add_i32 s34, 0, 0x10000
	s_cmp_eq_u32 s21, 28
	s_cselect_b32 s17, s61, s13
	s_cselect_b32 s16, s60, s12
	v_add_u32_e32 v0, s34, v212
	s_cselect_b32 s13, s31, s19
	s_cselect_b32 s12, s30, s18
	s_add_i32 s38, 0, 0x14000
	s_waitcnt lgkmcnt(0)
	ds_read_b128 v[132:135], v0
	ds_read_b128 v[136:139], v0 offset:1024
	ds_read_b128 v[140:143], v0 offset:2048
	ds_read_b128 v[144:147], v0 offset:3072
	v_add_u32_e32 v0, s38, v212
	ds_read_b128 v[148:151], v0
	ds_read_b128 v[152:155], v0 offset:1024
	ds_read_b128 v[184:187], v0 offset:2048
	ds_read_b128 v[188:191], v0 offset:3072
	v_lshl_add_u64 v[2:3], s[0:1], 0, v[180:181]
	s_add_i32 m0, s88, 0xc000
	ds_read_b128 v[192:195], v216
	ds_read_b128 v[196:199], v216 offset:1024
	ds_read_b128 v[200:203], v216 offset:2048
	ds_read_b128 v[204:207], v216 offset:3072
	ds_read_b128 v[218:221], v216 offset:4096
	ds_read_b128 v[222:225], v216 offset:5120
	ds_read_b128 v[226:229], v216 offset:6144
	ds_read_b128 v[230:233], v216 offset:7168
	global_load_lds_dwordx4 v[2:3], off
	v_lshl_add_u64 v[2:3], s[0:1], 0, v[182:183]
	s_add_i32 m0, s88, 0xe000
	s_nop 0
	global_load_lds_dwordx4 v[2:3], off
	s_waitcnt vmcnt(8)
	s_waitcnt lgkmcnt(0)
	s_barrier
	s_setprio 1
	s_waitcnt lgkmcnt(0)
	v_mfma_f32_16x16x32_bf16 v[128:131], v[132:135], v[192:195], v[128:131]
	v_mfma_f32_16x16x32_bf16 v[124:127], v[140:143], v[192:195], v[124:127]
	v_mfma_f32_16x16x32_bf16 v[112:115], v[132:135], v[200:203], v[112:115]
	v_mfma_f32_16x16x32_bf16 v[108:111], v[140:143], v[200:203], v[108:111]
	v_mfma_f32_16x16x32_bf16 v[96:99], v[132:135], v[218:221], v[96:99]
	v_mfma_f32_16x16x32_bf16 v[92:95], v[140:143], v[218:221], v[92:95]
	v_mfma_f32_16x16x32_bf16 v[80:83], v[132:135], v[226:229], v[80:83]
	v_mfma_f32_16x16x32_bf16 v[76:79], v[140:143], v[226:229], v[76:79]
	v_mfma_f32_16x16x32_bf16 v[128:131], v[136:139], v[196:199], v[128:131]
	v_mfma_f32_16x16x32_bf16 v[124:127], v[144:147], v[196:199], v[124:127]
	v_mfma_f32_16x16x32_bf16 v[112:115], v[136:139], v[204:207], v[112:115]
	v_mfma_f32_16x16x32_bf16 v[108:111], v[144:147], v[204:207], v[108:111]
	v_mfma_f32_16x16x32_bf16 v[96:99], v[136:139], v[222:225], v[96:99]
	v_mfma_f32_16x16x32_bf16 v[92:95], v[144:147], v[222:225], v[92:95]
	v_mfma_f32_16x16x32_bf16 v[80:83], v[136:139], v[230:233], v[80:83]
	v_mfma_f32_16x16x32_bf16 v[76:79], v[144:147], v[230:233], v[76:79]
	v_mfma_f32_16x16x32_bf16 v[120:123], v[148:151], v[192:195], v[120:123]
	v_mfma_f32_16x16x32_bf16 v[116:119], v[184:187], v[192:195], v[116:119]
	v_mfma_f32_16x16x32_bf16 v[104:107], v[148:151], v[200:203], v[104:107]
	v_mfma_f32_16x16x32_bf16 v[100:103], v[184:187], v[200:203], v[100:103]
	v_mfma_f32_16x16x32_bf16 v[88:91], v[148:151], v[218:221], v[88:91]
	v_mfma_f32_16x16x32_bf16 v[84:87], v[184:187], v[218:221], v[84:87]
	v_mfma_f32_16x16x32_bf16 v[72:75], v[148:151], v[226:229], v[72:75]
	v_mfma_f32_16x16x32_bf16 v[68:71], v[184:187], v[226:229], v[68:71]
	v_mfma_f32_16x16x32_bf16 v[120:123], v[152:155], v[196:199], v[120:123]
	v_mfma_f32_16x16x32_bf16 v[116:119], v[188:191], v[196:199], v[116:119]
	v_mfma_f32_16x16x32_bf16 v[104:107], v[152:155], v[204:207], v[104:107]
	v_mfma_f32_16x16x32_bf16 v[100:103], v[188:191], v[204:207], v[100:103]
	v_mfma_f32_16x16x32_bf16 v[88:91], v[152:155], v[222:225], v[88:91]
	v_mfma_f32_16x16x32_bf16 v[84:87], v[188:191], v[222:225], v[84:87]
	v_mfma_f32_16x16x32_bf16 v[72:75], v[152:155], v[230:233], v[72:75]
	v_mfma_f32_16x16x32_bf16 v[68:71], v[188:191], v[230:233], v[68:71]
	s_setprio 0
	s_barrier
	s_add_i32 s34, s34, s87
	v_lshl_add_u64 v[208:209], s[12:13], 0, v[158:159]
	s_mov_b32 m0, s34
	ds_read_b128 v[192:195], v216 offset:16384
	ds_read_b128 v[196:199], v216 offset:17408
	ds_read_b128 v[200:203], v216 offset:18432
	ds_read_b128 v[204:207], v216 offset:19456
	ds_read_b128 v[218:221], v216 offset:20480
	ds_read_b128 v[222:225], v216 offset:21504
	ds_read_b128 v[226:229], v216 offset:22528
	ds_read_b128 v[230:233], v216 offset:23552
	global_load_lds_dwordx4 v[208:209], off
	s_add_i32 m0, s34, 0x2000
	s_add_u32 s34, s12, 0x20000
	v_lshl_add_u64 v[234:235], s[12:13], 0, v[174:175]
	s_addc_u32 s35, s13, 0
	s_add_i32 s38, s38, s87
	global_load_lds_dwordx4 v[234:235], off
	v_lshl_add_u64 v[2:3], s[34:35], 0, v[158:159]
	s_mov_b32 m0, s38
	v_lshl_add_u64 v[236:237], s[16:17], 0, v[156:157]
	global_load_lds_dwordx4 v[2:3], off
	v_lshl_add_u64 v[2:3], s[34:35], 0, v[174:175]
	s_add_i32 m0, s38, 0x2000
	v_lshl_add_u64 v[238:239], s[16:17], 0, v[160:161]
	global_load_lds_dwordx4 v[2:3], off
	s_mov_b32 m0, s88
	s_nop 0
	global_load_lds_dwordx4 v[236:237], off
	s_mov_b32 m0, s89
	s_nop 0
	global_load_lds_dwordx4 v[238:239], off
	s_waitcnt vmcnt(8)
	s_waitcnt lgkmcnt(0)
	s_barrier
; #define PG8_STAGE(bufoff, gbase, voff) do { _Pragma("unroll") for (int _i = 0; _i < 2; ++_i) \
;         __builtin_amdgcn_global_load_lds((const __attribute__((address_space(1))) unsigned*)((const char*)(gbase) + (voff)[_i]), (LAS unsigned*)(lds + (bufoff) + ldsw + _i * 8192), 16, 0, 0); } while (0)
; #define PG8_LDA(dst, b, h) do { _Pragma("unroll") for (int m = 0; m < 4; ++m) _Pragma("unroll") for (int k = 0; k < 2; ++k) dst[m][k] = *(const LAS bf16x8*)(lds + PG8_SA(b, h) + aoff + m * 2048 + k * 1024); } while (0)
; #define PG8_LDB(dst, b, h) do { _Pragma("unroll") for (int n = 0; n < 2; ++n) _Pragma("unroll") for (int k = 0; k < 2; ++k) dst[n][k] = *(const LAS bf16x8*)(lds + PG8_SB(b, h) + boff + n * 2048 + k * 1024); } while (0)
; #define PG8_MMA(ai, bj, At, Bt) do { __builtin_amdgcn_s_setprio(1); _Pragma("unroll") for (int m = 0; m < 4; ++m) _Pragma("unroll") for (int n = 0; n < 2; ++n) _Pragma("unroll") for (int k = 0; k < 2; ++k) \
;         acc[ai][bj][m][n] = __builtin_amdgcn_mfma_f32_16x16x32_bf16(Bt[n][k], At[m][k], acc[ai][bj][m][n], 0, 0, 0); __builtin_amdgcn_s_setprio(0); } while (0)
; #define PG8_WAIT_V(n) asm volatile("s_waitcnt vmcnt(" #n ")" ::: "memory")
; #define PG8_WAIT_L(n) asm volatile("s_waitcnt lgkmcnt(" #n ")" ::: "memory")
; #define PG8_BAR __builtin_amdgcn_s_barrier()
; #define PG8_SCHED __builtin_amdgcn_sched_barrier(0)
; template <class Epi, class SchedT, bool ALIGN_EPI, bool SP2>
; __device__ __forceinline__ void gemm_phase(LAS unsigned char* lds, const int ldk, const int nt, const SchedT& S, const Epi& E) {
;     ...
;             PG8_WAIT_V(8); PG8_WAIT_L(0); PG8_BAR; PG8_MMA(1, 0, At, B0); PG8_MMA(1, 1, At, B1); PG8_BAR; PG8_SCHED;
;             PG8_LDB(B0, 1, 0); PG8_LDB(B1, 1, 1); PG8_SCHED; PG8_LDA(At, 1, 0); PG8_STAGE(PG8_SA(0, 1), a2 + hstep, voffA);
;             PG8_WAIT_V(8); PG8_WAIT_L(0); PG8_BAR; PG8_MMA(0, 0, At, B0); PG8_MMA(0, 1, At, B1); PG8_BAR; PG8_SCHED;
	s_setprio 1
	s_waitcnt lgkmcnt(0)
	v_mfma_f32_16x16x32_bf16 v[64:67], v[132:135], v[192:195], v[64:67]
	v_mfma_f32_16x16x32_bf16 v[60:63], v[140:143], v[192:195], v[60:63]
	v_mfma_f32_16x16x32_bf16 v[48:51], v[132:135], v[200:203], v[48:51]
	v_mfma_f32_16x16x32_bf16 v[44:47], v[140:143], v[200:203], v[44:47]
	v_mfma_f32_16x16x32_bf16 v[32:35], v[132:135], v[218:221], v[32:35]
	v_mfma_f32_16x16x32_bf16 v[28:31], v[140:143], v[218:221], v[28:31]
	v_mfma_f32_16x16x32_bf16 v[16:19], v[132:135], v[226:229], v[16:19]
	v_mfma_f32_16x16x32_bf16 v[12:15], v[140:143], v[226:229], v[12:15]
	v_mfma_f32_16x16x32_bf16 v[64:67], v[136:139], v[196:199], v[64:67]
	v_mfma_f32_16x16x32_bf16 v[60:63], v[144:147], v[196:199], v[60:63]
	v_mfma_f32_16x16x32_bf16 v[48:51], v[136:139], v[204:207], v[48:51]
	v_mfma_f32_16x16x32_bf16 v[44:47], v[144:147], v[204:207], v[44:47]
	v_mfma_f32_16x16x32_bf16 v[32:35], v[136:139], v[222:225], v[32:35]
	v_mfma_f32_16x16x32_bf16 v[28:31], v[144:147], v[222:225], v[28:31]
	v_mfma_f32_16x16x32_bf16 v[16:19], v[136:139], v[230:233], v[16:19]
	v_mfma_f32_16x16x32_bf16 v[12:15], v[144:147], v[230:233], v[12:15]
	v_mfma_f32_16x16x32_bf16 v[56:59], v[148:151], v[192:195], v[56:59]
	v_mfma_f32_16x16x32_bf16 v[52:55], v[184:187], v[192:195], v[52:55]
	v_mfma_f32_16x16x32_bf16 v[40:43], v[148:151], v[200:203], v[40:43]
	v_mfma_f32_16x16x32_bf16 v[36:39], v[184:187], v[200:203], v[36:39]
	v_mfma_f32_16x16x32_bf16 v[24:27], v[148:151], v[218:221], v[24:27]
	v_mfma_f32_16x16x32_bf16 v[20:23], v[184:187], v[218:221], v[20:23]
	v_mfma_f32_16x16x32_bf16 v[8:11], v[148:151], v[226:229], v[8:11]
	v_mfma_f32_16x16x32_bf16 v[2:5], v[184:187], v[226:229], v[4:7]
	v_mfma_f32_16x16x32_bf16 v[56:59], v[152:155], v[196:199], v[56:59]
	v_mfma_f32_16x16x32_bf16 v[52:55], v[188:191], v[196:199], v[52:55]
	v_mfma_f32_16x16x32_bf16 v[40:43], v[152:155], v[204:207], v[40:43]
	v_mfma_f32_16x16x32_bf16 v[36:39], v[188:191], v[204:207], v[36:39]
	v_mfma_f32_16x16x32_bf16 v[24:27], v[152:155], v[222:225], v[24:27]
	v_mfma_f32_16x16x32_bf16 v[20:23], v[188:191], v[222:225], v[20:23]
	v_mfma_f32_16x16x32_bf16 v[8:11], v[152:155], v[230:233], v[8:11]
	v_mfma_f32_16x16x32_bf16 v[2:5], v[188:191], v[230:233], v[2:5]
	s_setprio 0
	s_barrier
	s_add_i32 s34, 0, 0x18000
	v_add_u32_e32 v0, s34, v212
	s_add_i32 s35, 0, 0x1c000
	ds_read_b128 v[132:135], v0
	ds_read_b128 v[136:139], v0 offset:1024
	ds_read_b128 v[140:143], v0 offset:2048
	ds_read_b128 v[144:147], v0 offset:3072
	v_add_u32_e32 v0, s35, v212
	ds_read_b128 v[148:151], v0
	ds_read_b128 v[152:155], v0 offset:1024
	ds_read_b128 v[184:187], v0 offset:2048
	ds_read_b128 v[188:191], v0 offset:3072
	s_add_u32 s16, s16, 0x80000
	s_addc_u32 s17, s17, 0
	s_mov_b32 m0, s90
	v_lshl_add_u64 v[6:7], s[16:17], 0, v[156:157]
	ds_read_b128 v[192:195], v216 offset:32768
	ds_read_b128 v[196:199], v216 offset:33792
	ds_read_b128 v[200:203], v216 offset:34816
	ds_read_b128 v[204:207], v216 offset:35840
	ds_read_b128 v[218:221], v216 offset:36864
	ds_read_b128 v[222:225], v216 offset:37888
	ds_read_b128 v[226:229], v216 offset:38912
	ds_read_b128 v[230:233], v216 offset:39936
	global_load_lds_dwordx4 v[6:7], off
	v_lshl_add_u64 v[6:7], s[16:17], 0, v[160:161]
	s_mov_b32 m0, s91
	s_nop 0
	global_load_lds_dwordx4 v[6:7], off
	s_waitcnt vmcnt(8)
	s_waitcnt lgkmcnt(0)
	s_barrier
	s_setprio 1
	s_waitcnt lgkmcnt(0)
	v_mfma_f32_16x16x32_bf16 v[128:131], v[132:135], v[192:195], v[128:131]
	v_mfma_f32_16x16x32_bf16 v[124:127], v[140:143], v[192:195], v[124:127]
	v_mfma_f32_16x16x32_bf16 v[112:115], v[132:135], v[200:203], v[112:115]
	v_mfma_f32_16x16x32_bf16 v[108:111], v[140:143], v[200:203], v[108:111]
	v_mfma_f32_16x16x32_bf16 v[96:99], v[132:135], v[218:221], v[96:99]
	v_mfma_f32_16x16x32_bf16 v[92:95], v[140:143], v[218:221], v[92:95]
	v_mfma_f32_16x16x32_bf16 v[80:83], v[132:135], v[226:229], v[80:83]
	v_mfma_f32_16x16x32_bf16 v[76:79], v[140:143], v[226:229], v[76:79]
	v_mfma_f32_16x16x32_bf16 v[128:131], v[136:139], v[196:199], v[128:131]
	v_mfma_f32_16x16x32_bf16 v[124:127], v[144:147], v[196:199], v[124:127]
	v_mfma_f32_16x16x32_bf16 v[112:115], v[136:139], v[204:207], v[112:115]
	v_mfma_f32_16x16x32_bf16 v[108:111], v[144:147], v[204:207], v[108:111]
	v_mfma_f32_16x16x32_bf16 v[96:99], v[136:139], v[222:225], v[96:99]
	v_mfma_f32_16x16x32_bf16 v[92:95], v[144:147], v[222:225], v[92:95]
	v_mfma_f32_16x16x32_bf16 v[80:83], v[136:139], v[230:233], v[80:83]
	v_mfma_f32_16x16x32_bf16 v[76:79], v[144:147], v[230:233], v[76:79]
	v_mfma_f32_16x16x32_bf16 v[120:123], v[148:151], v[192:195], v[120:123]
	v_mfma_f32_16x16x32_bf16 v[116:119], v[184:187], v[192:195], v[116:119]
	v_mfma_f32_16x16x32_bf16 v[104:107], v[148:151], v[200:203], v[104:107]
	v_mfma_f32_16x16x32_bf16 v[100:103], v[184:187], v[200:203], v[100:103]
	v_mfma_f32_16x16x32_bf16 v[88:91], v[148:151], v[218:221], v[88:91]
	v_mfma_f32_16x16x32_bf16 v[84:87], v[184:187], v[218:221], v[84:87]
	v_mfma_f32_16x16x32_bf16 v[72:75], v[148:151], v[226:229], v[72:75]
	v_mfma_f32_16x16x32_bf16 v[68:71], v[184:187], v[226:229], v[68:71]
	v_mfma_f32_16x16x32_bf16 v[120:123], v[152:155], v[196:199], v[120:123]
	v_mfma_f32_16x16x32_bf16 v[116:119], v[188:191], v[196:199], v[116:119]
	v_mfma_f32_16x16x32_bf16 v[104:107], v[152:155], v[204:207], v[104:107]
	v_mfma_f32_16x16x32_bf16 v[100:103], v[188:191], v[204:207], v[100:103]
	v_mfma_f32_16x16x32_bf16 v[88:91], v[152:155], v[222:225], v[88:91]
	v_mfma_f32_16x16x32_bf16 v[84:87], v[188:191], v[222:225], v[84:87]
	v_mfma_f32_16x16x32_bf16 v[72:75], v[152:155], v[230:233], v[72:75]
	v_mfma_f32_16x16x32_bf16 v[68:71], v[188:191], v[230:233], v[68:71]
	s_setprio 0
	s_barrier
; #define PG8_STAGE(bufoff, gbase, voff) do { _Pragma("unroll") for (int _i = 0; _i < 2; ++_i) \
;         __builtin_amdgcn_global_load_lds((const __attribute__((address_space(1))) unsigned*)((const char*)(gbase) + (voff)[_i]), (LAS unsigned*)(lds + (bufoff) + ldsw + _i * 8192), 16, 0, 0); } while (0)
; #define PG8_LDA(dst, b, h) do { _Pragma("unroll") for (int m = 0; m < 4; ++m) _Pragma("unroll") for (int k = 0; k < 2; ++k) dst[m][k] = *(const LAS bf16x8*)(lds + PG8_SA(b, h) + aoff + m * 2048 + k * 1024); } while (0)
; #define PG8_MMA(ai, bj, At, Bt) do { __builtin_amdgcn_s_setprio(1); _Pragma("unroll") for (int m = 0; m < 4; ++m) _Pragma("unroll") for (int n = 0; n < 2; ++n) _Pragma("unroll") for (int k = 0; k < 2; ++k) \
;         acc[ai][bj][m][n] = __builtin_amdgcn_mfma_f32_16x16x32_bf16(Bt[n][k], At[m][k], acc[ai][bj][m][n], 0, 0, 0); __builtin_amdgcn_s_setprio(0); } while (0)
; #define PG8_WAIT_V(n) asm volatile("s_waitcnt vmcnt(" #n ")" ::: "memory")
; #define PG8_WAIT_L(n) asm volatile("s_waitcnt lgkmcnt(" #n ")" ::: "memory")
; #define PG8_BAR __builtin_amdgcn_s_barrier()
; #define PG8_SCHED __builtin_amdgcn_sched_barrier(0)
; template <class Epi, class SchedT, bool ALIGN_EPI, bool SP2>
; __device__ __forceinline__ void gemm_phase(LAS unsigned char* lds, const int ldk, const int nt, const SchedT& S, const Epi& E) {
;     ...
;             PG8_LDA(At, 1, 1); PG8_STAGE(PG8_SB(1, 0), b3, voffB); PG8_STAGE(PG8_SB(1, 1), b3 + hstepB, voffB); PG8_STAGE(PG8_SA(1, 0), a3, voffA);
;             PG8_WAIT_V(8); PG8_WAIT_L(0); PG8_BAR; PG8_MMA(1, 0, At, B0); PG8_MMA(1, 1, At, B1); PG8_BAR; PG8_SCHED;
;     ...
;         if constexpr (ALIGN_EPI) { if (wr == 0) PG8_BAR; }
	s_add_i32 s16, s34, s87
	v_lshl_add_u64 v[6:7], v[208:209], 0, s[24:25]
	s_mov_b32 m0, s16
	ds_read_b128 v[192:195], v216 offset:49152
	ds_read_b128 v[196:199], v216 offset:50176
	ds_read_b128 v[200:203], v216 offset:51200
	ds_read_b128 v[204:207], v216 offset:52224
	ds_read_b128 v[218:221], v216 offset:53248
	ds_read_b128 v[222:225], v216 offset:54272
	ds_read_b128 v[226:229], v216 offset:55296
	ds_read_b128 v[230:233], v216 offset:56320
	global_load_lds_dwordx4 v[6:7], off
	s_add_i32 m0, s16, 0x2000
	s_add_u32 s12, s12, 0x20080
	v_lshl_add_u64 v[6:7], v[234:235], 0, s[24:25]
	s_addc_u32 s13, s13, 0
	s_add_i32 s16, s35, s87
	global_load_lds_dwordx4 v[6:7], off
	v_lshl_add_u64 v[6:7], s[12:13], 0, v[158:159]
	s_mov_b32 m0, s16
	s_nop 0
	global_load_lds_dwordx4 v[6:7], off
	v_lshl_add_u64 v[6:7], s[12:13], 0, v[174:175]
	s_add_i32 m0, s16, 0x2000
	s_nop 0
	global_load_lds_dwordx4 v[6:7], off
	v_lshl_add_u64 v[6:7], v[236:237], 0, s[24:25]
	s_mov_b32 m0, s92
	s_nop 0
	global_load_lds_dwordx4 v[6:7], off
	v_lshl_add_u64 v[6:7], v[238:239], 0, s[24:25]
	s_mov_b32 m0, s93
	s_nop 0
	global_load_lds_dwordx4 v[6:7], off
	s_waitcnt vmcnt(8)
	s_waitcnt lgkmcnt(0)
	s_barrier
	s_setprio 1
	s_waitcnt lgkmcnt(0)
	v_mfma_f32_16x16x32_bf16 v[64:67], v[132:135], v[192:195], v[64:67]
	v_mfma_f32_16x16x32_bf16 v[60:63], v[140:143], v[192:195], v[60:63]
	v_mfma_f32_16x16x32_bf16 v[48:51], v[132:135], v[200:203], v[48:51]
	v_mfma_f32_16x16x32_bf16 v[44:47], v[140:143], v[200:203], v[44:47]
	v_mfma_f32_16x16x32_bf16 v[32:35], v[132:135], v[218:221], v[32:35]
	v_mfma_f32_16x16x32_bf16 v[28:31], v[140:143], v[218:221], v[28:31]
	v_mfma_f32_16x16x32_bf16 v[16:19], v[132:135], v[226:229], v[16:19]
	v_mfma_f32_16x16x32_bf16 v[12:15], v[140:143], v[226:229], v[12:15]
	v_mfma_f32_16x16x32_bf16 v[64:67], v[136:139], v[196:199], v[64:67]
	v_mfma_f32_16x16x32_bf16 v[60:63], v[144:147], v[196:199], v[60:63]
	v_mfma_f32_16x16x32_bf16 v[48:51], v[136:139], v[204:207], v[48:51]
	v_mfma_f32_16x16x32_bf16 v[44:47], v[144:147], v[204:207], v[44:47]
	v_mfma_f32_16x16x32_bf16 v[32:35], v[136:139], v[222:225], v[32:35]
	v_mfma_f32_16x16x32_bf16 v[28:31], v[144:147], v[222:225], v[28:31]
	v_mfma_f32_16x16x32_bf16 v[16:19], v[136:139], v[230:233], v[16:19]
	v_mfma_f32_16x16x32_bf16 v[12:15], v[144:147], v[230:233], v[12:15]
	v_mfma_f32_16x16x32_bf16 v[56:59], v[148:151], v[192:195], v[56:59]
	v_mfma_f32_16x16x32_bf16 v[52:55], v[184:187], v[192:195], v[52:55]
	v_mfma_f32_16x16x32_bf16 v[40:43], v[148:151], v[200:203], v[40:43]
	v_mfma_f32_16x16x32_bf16 v[36:39], v[184:187], v[200:203], v[36:39]
	v_mfma_f32_16x16x32_bf16 v[24:27], v[148:151], v[218:221], v[24:27]
	v_mfma_f32_16x16x32_bf16 v[20:23], v[184:187], v[218:221], v[20:23]
	v_mfma_f32_16x16x32_bf16 v[6:9], v[148:151], v[226:229], v[8:11]
	v_mfma_f32_16x16x32_bf16 v[2:5], v[184:187], v[226:229], v[2:5]
	v_mfma_f32_16x16x32_bf16 v[56:59], v[152:155], v[196:199], v[56:59]
	v_mfma_f32_16x16x32_bf16 v[52:55], v[188:191], v[196:199], v[52:55]
	v_mfma_f32_16x16x32_bf16 v[40:43], v[152:155], v[204:207], v[40:43]
	v_mfma_f32_16x16x32_bf16 v[36:39], v[188:191], v[204:207], v[36:39]
	v_mfma_f32_16x16x32_bf16 v[24:27], v[152:155], v[222:225], v[24:27]
	v_mfma_f32_16x16x32_bf16 v[20:23], v[188:191], v[222:225], v[20:23]
	v_mfma_f32_16x16x32_bf16 v[8:11], v[152:155], v[230:233], v[6:9]
	v_mfma_f32_16x16x32_bf16 v[4:7], v[188:191], v[230:233], v[2:5]
	s_setprio 0
	s_barrier
	s_add_i32 s21, s21, 2
	s_add_u32 s0, s0, 0x100
	s_addc_u32 s1, s1, 0
	s_add_u32 s18, s18, 0x100
	s_addc_u32 s19, s19, 0
	s_cmp_gt_u32 s21, 29
	s_cbranch_scc0 .LBB0_123
	s_and_b64 vcc, exec, s[58:59]
	s_cbranch_vccz .LBB0_126
	s_barrier
	s_setprio 3

; #define PG8_WAIT_V(n) asm volatile("s_waitcnt vmcnt(" #n ")" ::: "memory")
; #define PG8_BAR __builtin_amdgcn_s_barrier()
; template <class Epi, class SchedT, bool ALIGN_EPI, bool SP2>
; __device__ __forceinline__ void gemm_phase(LAS unsigned char* lds, const int ldk, const int nt, const SchedT& S, const Epi& E) {
;     ...
;     PG8_WAIT_V(0);
;     if constexpr (!ALIGN_EPI) { if (wr == 0) PG8_BAR; }
;     PG8_BAR;
.LBB0_357:
	s_setprio 0
	s_waitcnt vmcnt(0)
	v_readlane_b32 s88, v163, 21
	v_readlane_b32 s90, v163, 27
	v_readlane_b32 s84, v163, 29
	v_readlane_b32 s60, v163, 31
	v_readlane_b32 s74, v163, 20
	v_readlane_b32 s89, v163, 22
	v_readlane_b32 s80, v163, 23
	v_readlane_b32 s75, v163, 25
	v_readlane_b32 s93, v163, 26
	v_readlane_b32 s91, v163, 28
	v_readlane_b32 s85, v163, 30
	v_readlane_b32 s61, v163, 32
	v_readlane_b32 s92, v163, 33
	v_readlane_b32 s52, v163, 34
	v_readlane_b32 s53, v163, 35
	s_movk_i32 s54, 0x2000
	s_movk_i32 s55, 0x4000
	s_movk_i32 s56, 0x6000
	s_mov_b32 s57, 0x18000
	s_mov_b32 s58, 0x8000
	s_movk_i32 s94, 0x1000
	s_movk_i32 s95, 0x3000
	s_mov_b32 s86, 0x20000
	s_mov_b32 s87, 0x28000
	s_mov_b32 s50, 0x30000
	s_barrier
	v_readlane_b32 s81, v163, 24

; #define PG8_BAR __builtin_amdgcn_s_barrier()
; template <class Epi, class SchedT, bool ALIGN_EPI, bool SP2>
; __device__ __forceinline__ void gemm_phase(LAS unsigned char* lds, const int ldk, const int nt, const SchedT& S, const Epi& E) {
;     ...
;         if constexpr (ALIGN_EPI) { if (wr == 0) PG8_BAR; }
.Lp3e_align:
	s_and_b64 vcc, exec, s[44:45]
	s_cbranch_vccz .LBB0_537
	s_barrier
	s_setprio 3

; #define PG8_WAIT_V(n) asm volatile("s_waitcnt vmcnt(" #n ")" ::: "memory")
; #define PG8_BAR __builtin_amdgcn_s_barrier()
; template <class Epi, class SchedT, bool ALIGN_EPI, bool SP2>
; __device__ __forceinline__ void gemm_phase(LAS unsigned char* lds, const int ldk, const int nt, const SchedT& S, const Epi& E) {
;     ...
;     PG8_WAIT_V(0);
;     if constexpr (!ALIGN_EPI) { if (wr == 0) PG8_BAR; }
;     PG8_BAR;
.LBB0_606:
	s_setprio 0
	s_waitcnt vmcnt(0)
	v_readlane_b32 s60, v163, 31
	v_readlane_b32 s61, v163, 32
	s_barrier

; #define PG8_STAGE(bufoff, gbase, voff) do { _Pragma("unroll") for (int _i = 0; _i < 2; ++_i) \
;         __builtin_amdgcn_global_load_lds((const __attribute__((address_space(1))) unsigned*)((const char*)(gbase) + (voff)[_i]), (LAS unsigned*)(lds + (bufoff) + ldsw + _i * 8192), 16, 0, 0); } while (0)
; #define PG8_LDA(dst, b, h) do { _Pragma("unroll") for (int m = 0; m < 4; ++m) _Pragma("unroll") for (int k = 0; k < 2; ++k) dst[m][k] = *(const LAS bf16x8*)(lds + PG8_SA(b, h) + aoff + m * 2048 + k * 1024); } while (0)
; #define PG8_LDB(dst, b, h) do { _Pragma("unroll") for (int n = 0; n < 2; ++n) _Pragma("unroll") for (int k = 0; k < 2; ++k) dst[n][k] = *(const LAS bf16x8*)(lds + PG8_SB(b, h) + boff + n * 2048 + k * 1024); } while (0)
; #define PG8_MMA(ai, bj, At, Bt) do { __builtin_amdgcn_s_setprio(1); _Pragma("unroll") for (int m = 0; m < 4; ++m) _Pragma("unroll") for (int n = 0; n < 2; ++n) _Pragma("unroll") for (int k = 0; k < 2; ++k) \
;         acc[ai][bj][m][n] = __builtin_amdgcn_mfma_f32_16x16x32_bf16(Bt[n][k], At[m][k], acc[ai][bj][m][n], 0, 0, 0); __builtin_amdgcn_s_setprio(0); } while (0)
; #define PG8_WAIT_V(n) asm volatile("s_waitcnt vmcnt(" #n ")" ::: "memory")
; #define PG8_WAIT_L(n) asm volatile("s_waitcnt lgkmcnt(" #n ")" ::: "memory")
; #define PG8_BAR __builtin_amdgcn_s_barrier()
; #define PG8_SCHED __builtin_amdgcn_sched_barrier(0)
; template <class Epi, class SchedT, bool ALIGN_EPI, bool SP2>
; __device__ __forceinline__ void gemm_phase(LAS unsigned char* lds, const int ldk, const int nt, const SchedT& S, const Epi& E) {
;     ...
;             const bool last = (t == nt - 2);
;             const char* a1 = cA + (size_t)(t + 1) * kstep;
;             const char* a2 = last ? nA : cA + (size_t)(t + 2) * kstep; const char* b2 = last ? nB : cB + (size_t)(t + 2) * kstep;
;             const char* a3 = a2 + kstep; const char* b3 = b2 + kstep;
;             if constexpr (SP2) {
;             PG8_LDB(B0, 0, 0); PG8_LDB(B1, 0, 1); PG8_SCHED; PG8_LDA(At, 0, 0); PG8_STAGE(PG8_SA(1, 1), a1 + hstep, voffA);
;             PG8_WAIT_V(8); PG8_WAIT_L(0); PG8_BAR; PG8_MMA(0, 0, At, B0); PG8_MMA(0, 1, At, B1); PG8_BAR; PG8_SCHED;
;             PG8_LDA(At, 0, 1); PG8_STAGE(PG8_SB(0, 0), b2, voffB); PG8_STAGE(PG8_SB(0, 1), b2 + hstepB, voffB); PG8_STAGE(PG8_SA(0, 0), a2, voffA);
.LBB0_668:
	s_add_u32 s36, s34, 0xfff80080
	s_addc_u32 s37, s35, -1
	s_add_i32 s51, 0, 0x10000
	s_cmp_eq_u32 s22, 28
	s_cselect_b32 s57, s1, s37
	s_cselect_b32 s56, s0, s36
	v_add_u32_e32 v144, s51, v147
	s_cselect_b32 s37, s55, s20
	s_cselect_b32 s36, s54, s13
	s_add_i32 s53, 0, 0x14000
	ds_read_b128 v[140:143], v144
	ds_read_b128 v[150:153], v144 offset:1024
	ds_read_b128 v[154:157], v144 offset:2048
	ds_read_b128 v[158:161], v144 offset:3072
	v_add_u32_e32 v144, s53, v147
	ds_read_b128 v[174:177], v144
	ds_read_b128 v[178:181], v144 offset:1024
	ds_read_b128 v[182:185], v144 offset:2048
	ds_read_b128 v[186:189], v144 offset:3072
	v_lshl_add_u64 v[144:145], s[34:35], 0, v[136:137]
	s_add_i32 m0, s17, 0xc000
	ds_read_b128 v[190:193], v149
	ds_read_b128 v[194:197], v149 offset:1024
	ds_read_b128 v[198:201], v149 offset:2048
	ds_read_b128 v[202:205], v149 offset:3072
	ds_read_b128 v[206:209], v149 offset:4096
	ds_read_b128 v[210:213], v149 offset:5120
	ds_read_b128 v[214:217], v149 offset:6144
	ds_read_b128 v[218:221], v149 offset:7168
	global_load_lds_dwordx4 v[144:145], off
	v_lshl_add_u64 v[144:145], s[34:35], 0, v[138:139]
	s_add_i32 m0, s17, 0xe000
	s_nop 0
	global_load_lds_dwordx4 v[144:145], off
	s_waitcnt vmcnt(8)
	s_waitcnt lgkmcnt(0)
	s_barrier
	s_setprio 1
	s_waitcnt lgkmcnt(0)
	v_mfma_f32_16x16x32_bf16 v[126:129], v[140:143], v[190:193], v[126:129]
	v_mfma_f32_16x16x32_bf16 v[122:125], v[154:157], v[190:193], v[122:125]
	v_mfma_f32_16x16x32_bf16 v[110:113], v[140:143], v[198:201], v[110:113]
	v_mfma_f32_16x16x32_bf16 v[106:109], v[154:157], v[198:201], v[106:109]
	v_mfma_f32_16x16x32_bf16 v[94:97], v[140:143], v[206:209], v[94:97]
	v_mfma_f32_16x16x32_bf16 v[90:93], v[154:157], v[206:209], v[90:93]
	v_mfma_f32_16x16x32_bf16 v[78:81], v[140:143], v[214:217], v[78:81]
	v_mfma_f32_16x16x32_bf16 v[74:77], v[154:157], v[214:217], v[74:77]
	v_mfma_f32_16x16x32_bf16 v[126:129], v[150:153], v[194:197], v[126:129]
	v_mfma_f32_16x16x32_bf16 v[122:125], v[158:161], v[194:197], v[122:125]
	v_mfma_f32_16x16x32_bf16 v[110:113], v[150:153], v[202:205], v[110:113]
	v_mfma_f32_16x16x32_bf16 v[106:109], v[158:161], v[202:205], v[106:109]
	v_mfma_f32_16x16x32_bf16 v[94:97], v[150:153], v[210:213], v[94:97]
	v_mfma_f32_16x16x32_bf16 v[90:93], v[158:161], v[210:213], v[90:93]
	v_mfma_f32_16x16x32_bf16 v[78:81], v[150:153], v[218:221], v[78:81]
	v_mfma_f32_16x16x32_bf16 v[74:77], v[158:161], v[218:221], v[74:77]
	v_mfma_f32_16x16x32_bf16 v[118:121], v[174:177], v[190:193], v[118:121]
	v_mfma_f32_16x16x32_bf16 v[114:117], v[182:185], v[190:193], v[114:117]
	v_mfma_f32_16x16x32_bf16 v[102:105], v[174:177], v[198:201], v[102:105]
	v_mfma_f32_16x16x32_bf16 v[98:101], v[182:185], v[198:201], v[98:101]
	v_mfma_f32_16x16x32_bf16 v[86:89], v[174:177], v[206:209], v[86:89]
	v_mfma_f32_16x16x32_bf16 v[82:85], v[182:185], v[206:209], v[82:85]
	v_mfma_f32_16x16x32_bf16 v[70:73], v[174:177], v[214:217], v[70:73]
	v_mfma_f32_16x16x32_bf16 v[66:69], v[182:185], v[214:217], v[66:69]
	v_mfma_f32_16x16x32_bf16 v[118:121], v[178:181], v[194:197], v[118:121]
	v_mfma_f32_16x16x32_bf16 v[114:117], v[186:189], v[194:197], v[114:117]
	v_mfma_f32_16x16x32_bf16 v[102:105], v[178:181], v[202:205], v[102:105]
	v_mfma_f32_16x16x32_bf16 v[98:101], v[186:189], v[202:205], v[98:101]
	v_mfma_f32_16x16x32_bf16 v[86:89], v[178:181], v[210:213], v[86:89]
	v_mfma_f32_16x16x32_bf16 v[82:85], v[186:189], v[210:213], v[82:85]
	v_mfma_f32_16x16x32_bf16 v[70:73], v[178:181], v[218:221], v[70:73]
	v_mfma_f32_16x16x32_bf16 v[66:69], v[186:189], v[218:221], v[66:69]
	s_setprio 0
	s_barrier
	s_add_i32 s51, s51, s61
	v_lshl_add_u64 v[144:145], s[36:37], 0, v[0:1]
	s_mov_b32 m0, s51
	ds_read_b128 v[190:193], v149 offset:16384
	ds_read_b128 v[194:197], v149 offset:17408
	ds_read_b128 v[198:201], v149 offset:18432
	ds_read_b128 v[202:205], v149 offset:19456
	ds_read_b128 v[206:209], v149 offset:20480
	ds_read_b128 v[210:213], v149 offset:21504
	ds_read_b128 v[214:217], v149 offset:22528
	ds_read_b128 v[218:221], v149 offset:23552
	global_load_lds_dwordx4 v[144:145], off
	s_add_i32 m0, s51, 0x2000
	s_add_u32 s86, s36, 0x20000
	v_lshl_add_u64 v[222:223], s[36:37], 0, v[134:135]
	s_addc_u32 s87, s37, 0
	s_add_i32 s51, s53, s61
	global_load_lds_dwordx4 v[222:223], off
	v_lshl_add_u64 v[224:225], s[86:87], 0, v[0:1]
	s_mov_b32 m0, s51
	v_lshl_add_u64 v[226:227], s[56:57], 0, v[132:133]
	global_load_lds_dwordx4 v[224:225], off
	v_lshl_add_u64 v[224:225], s[86:87], 0, v[134:135]
	s_add_i32 m0, s51, 0x2000
	s_nop 0
	global_load_lds_dwordx4 v[224:225], off
	v_lshl_add_u64 v[224:225], s[56:57], 0, v[130:131]
	s_mov_b32 m0, s17
	s_nop 0
	global_load_lds_dwordx4 v[224:225], off
	s_mov_b32 m0, s62
	s_nop 0
	global_load_lds_dwordx4 v[226:227], off
	s_waitcnt vmcnt(8)
	s_waitcnt lgkmcnt(0)
	s_barrier
; #define PG8_STAGE(bufoff, gbase, voff) do { _Pragma("unroll") for (int _i = 0; _i < 2; ++_i) \
;         __builtin_amdgcn_global_load_lds((const __attribute__((address_space(1))) unsigned*)((const char*)(gbase) + (voff)[_i]), (LAS unsigned*)(lds + (bufoff) + ldsw + _i * 8192), 16, 0, 0); } while (0)
; #define PG8_LDA(dst, b, h) do { _Pragma("unroll") for (int m = 0; m < 4; ++m) _Pragma("unroll") for (int k = 0; k < 2; ++k) dst[m][k] = *(const LAS bf16x8*)(lds + PG8_SA(b, h) + aoff + m * 2048 + k * 1024); } while (0)
; #define PG8_LDB(dst, b, h) do { _Pragma("unroll") for (int n = 0; n < 2; ++n) _Pragma("unroll") for (int k = 0; k < 2; ++k) dst[n][k] = *(const LAS bf16x8*)(lds + PG8_SB(b, h) + boff + n * 2048 + k * 1024); } while (0)
; #define PG8_MMA(ai, bj, At, Bt) do { __builtin_amdgcn_s_setprio(1); _Pragma("unroll") for (int m = 0; m < 4; ++m) _Pragma("unroll") for (int n = 0; n < 2; ++n) _Pragma("unroll") for (int k = 0; k < 2; ++k) \
;         acc[ai][bj][m][n] = __builtin_amdgcn_mfma_f32_16x16x32_bf16(Bt[n][k], At[m][k], acc[ai][bj][m][n], 0, 0, 0); __builtin_amdgcn_s_setprio(0); } while (0)
; #define PG8_WAIT_V(n) asm volatile("s_waitcnt vmcnt(" #n ")" ::: "memory")
; #define PG8_WAIT_L(n) asm volatile("s_waitcnt lgkmcnt(" #n ")" ::: "memory")
; #define PG8_BAR __builtin_amdgcn_s_barrier()
; #define PG8_SCHED __builtin_amdgcn_sched_barrier(0)
; template <class Epi, class SchedT, bool ALIGN_EPI, bool SP2>
; __device__ __forceinline__ void gemm_phase(LAS unsigned char* lds, const int ldk, const int nt, const SchedT& S, const Epi& E) {
;     ...
;             PG8_WAIT_V(8); PG8_WAIT_L(0); PG8_BAR; PG8_MMA(1, 0, At, B0); PG8_MMA(1, 1, At, B1); PG8_BAR; PG8_SCHED;
;             PG8_LDB(B0, 1, 0); PG8_LDB(B1, 1, 1); PG8_SCHED; PG8_LDA(At, 1, 0); PG8_STAGE(PG8_SA(0, 1), a2 + hstep, voffA);
;             PG8_WAIT_V(8); PG8_WAIT_L(0); PG8_BAR; PG8_MMA(0, 0, At, B0); PG8_MMA(0, 1, At, B1); PG8_BAR; PG8_SCHED;
	s_setprio 1
	s_waitcnt lgkmcnt(0)
	v_mfma_f32_16x16x32_bf16 v[62:65], v[140:143], v[190:193], v[62:65]
	v_mfma_f32_16x16x32_bf16 v[58:61], v[154:157], v[190:193], v[58:61]
	v_mfma_f32_16x16x32_bf16 v[46:49], v[140:143], v[198:201], v[46:49]
	v_mfma_f32_16x16x32_bf16 v[42:45], v[154:157], v[198:201], v[42:45]
	v_mfma_f32_16x16x32_bf16 v[30:33], v[140:143], v[206:209], v[30:33]
	v_mfma_f32_16x16x32_bf16 v[26:29], v[154:157], v[206:209], v[26:29]
	v_mfma_f32_16x16x32_bf16 v[14:17], v[140:143], v[214:217], v[14:17]
	v_mfma_f32_16x16x32_bf16 v[10:13], v[154:157], v[214:217], v[10:13]
	v_mfma_f32_16x16x32_bf16 v[62:65], v[150:153], v[194:197], v[62:65]
	v_mfma_f32_16x16x32_bf16 v[58:61], v[158:161], v[194:197], v[58:61]
	v_mfma_f32_16x16x32_bf16 v[46:49], v[150:153], v[202:205], v[46:49]
	v_mfma_f32_16x16x32_bf16 v[42:45], v[158:161], v[202:205], v[42:45]
	v_mfma_f32_16x16x32_bf16 v[30:33], v[150:153], v[210:213], v[30:33]
	v_mfma_f32_16x16x32_bf16 v[26:29], v[158:161], v[210:213], v[26:29]
	v_mfma_f32_16x16x32_bf16 v[14:17], v[150:153], v[218:221], v[14:17]
	v_mfma_f32_16x16x32_bf16 v[10:13], v[158:161], v[218:221], v[10:13]
	v_mfma_f32_16x16x32_bf16 v[54:57], v[174:177], v[190:193], v[54:57]
	v_mfma_f32_16x16x32_bf16 v[50:53], v[182:185], v[190:193], v[50:53]
	v_mfma_f32_16x16x32_bf16 v[38:41], v[174:177], v[198:201], v[38:41]
	v_mfma_f32_16x16x32_bf16 v[34:37], v[182:185], v[198:201], v[34:37]
	v_mfma_f32_16x16x32_bf16 v[22:25], v[174:177], v[206:209], v[22:25]
	v_mfma_f32_16x16x32_bf16 v[18:21], v[182:185], v[206:209], v[18:21]
	v_mfma_f32_16x16x32_bf16 v[6:9], v[174:177], v[214:217], v[6:9]
	v_mfma_f32_16x16x32_bf16 v[2:5], v[182:185], v[214:217], v[2:5]
	v_mfma_f32_16x16x32_bf16 v[54:57], v[178:181], v[194:197], v[54:57]
	v_mfma_f32_16x16x32_bf16 v[50:53], v[186:189], v[194:197], v[50:53]
	v_mfma_f32_16x16x32_bf16 v[38:41], v[178:181], v[202:205], v[38:41]
	v_mfma_f32_16x16x32_bf16 v[34:37], v[186:189], v[202:205], v[34:37]
	v_mfma_f32_16x16x32_bf16 v[22:25], v[178:181], v[210:213], v[22:25]
	v_mfma_f32_16x16x32_bf16 v[18:21], v[186:189], v[210:213], v[18:21]
	v_mfma_f32_16x16x32_bf16 v[6:9], v[178:181], v[218:221], v[6:9]
	v_mfma_f32_16x16x32_bf16 v[2:5], v[186:189], v[218:221], v[2:5]
	s_setprio 0
	s_barrier
	s_add_i32 s51, 0, 0x18000
	s_add_i32 s53, 0, 0x1c000
	v_add_u32_e32 v158, s51, v147
	v_add_u32_e32 v186, s53, v147
	ds_read_b128 v[140:143], v158
	ds_read_b128 v[150:153], v158 offset:1024
	ds_read_b128 v[154:157], v158 offset:2048
	ds_read_b128 v[158:161], v158 offset:3072
	ds_read_b128 v[174:177], v186
	ds_read_b128 v[178:181], v186 offset:1024
	ds_read_b128 v[182:185], v186 offset:2048
	ds_read_b128 v[186:189], v186 offset:3072
	s_add_u32 s56, s56, 0x80000
	s_addc_u32 s57, s57, 0
	s_mov_b32 m0, s63
	v_lshl_add_u64 v[228:229], s[56:57], 0, v[130:131]
	ds_read_b128 v[190:193], v149 offset:32768
	ds_read_b128 v[194:197], v149 offset:33792
	ds_read_b128 v[198:201], v149 offset:34816
	ds_read_b128 v[202:205], v149 offset:35840
	ds_read_b128 v[206:209], v149 offset:36864
	ds_read_b128 v[210:213], v149 offset:37888
	ds_read_b128 v[214:217], v149 offset:38912
	ds_read_b128 v[218:221], v149 offset:39936
	global_load_lds_dwordx4 v[228:229], off
	v_lshl_add_u64 v[228:229], s[56:57], 0, v[132:133]
	s_mov_b32 m0, s81
	s_nop 0
	global_load_lds_dwordx4 v[228:229], off
	s_waitcnt vmcnt(8)
	s_waitcnt lgkmcnt(0)
	s_barrier
	s_setprio 1
	s_waitcnt lgkmcnt(0)
	v_mfma_f32_16x16x32_bf16 v[126:129], v[140:143], v[190:193], v[126:129]
	v_mfma_f32_16x16x32_bf16 v[122:125], v[154:157], v[190:193], v[122:125]
	v_mfma_f32_16x16x32_bf16 v[110:113], v[140:143], v[198:201], v[110:113]
	v_mfma_f32_16x16x32_bf16 v[106:109], v[154:157], v[198:201], v[106:109]
	v_mfma_f32_16x16x32_bf16 v[94:97], v[140:143], v[206:209], v[94:97]
	v_mfma_f32_16x16x32_bf16 v[90:93], v[154:157], v[206:209], v[90:93]
	v_mfma_f32_16x16x32_bf16 v[78:81], v[140:143], v[214:217], v[78:81]
	v_mfma_f32_16x16x32_bf16 v[74:77], v[154:157], v[214:217], v[74:77]
	v_mfma_f32_16x16x32_bf16 v[126:129], v[150:153], v[194:197], v[126:129]
	v_mfma_f32_16x16x32_bf16 v[122:125], v[158:161], v[194:197], v[122:125]
	v_mfma_f32_16x16x32_bf16 v[110:113], v[150:153], v[202:205], v[110:113]
	v_mfma_f32_16x16x32_bf16 v[106:109], v[158:161], v[202:205], v[106:109]
	v_mfma_f32_16x16x32_bf16 v[94:97], v[150:153], v[210:213], v[94:97]
	v_mfma_f32_16x16x32_bf16 v[90:93], v[158:161], v[210:213], v[90:93]
	v_mfma_f32_16x16x32_bf16 v[78:81], v[150:153], v[218:221], v[78:81]
	v_mfma_f32_16x16x32_bf16 v[74:77], v[158:161], v[218:221], v[74:77]
	v_mfma_f32_16x16x32_bf16 v[118:121], v[174:177], v[190:193], v[118:121]
	v_mfma_f32_16x16x32_bf16 v[114:117], v[182:185], v[190:193], v[114:117]
	v_mfma_f32_16x16x32_bf16 v[102:105], v[174:177], v[198:201], v[102:105]
	v_mfma_f32_16x16x32_bf16 v[98:101], v[182:185], v[198:201], v[98:101]
	v_mfma_f32_16x16x32_bf16 v[86:89], v[174:177], v[206:209], v[86:89]
	v_mfma_f32_16x16x32_bf16 v[82:85], v[182:185], v[206:209], v[82:85]
	v_mfma_f32_16x16x32_bf16 v[70:73], v[174:177], v[214:217], v[70:73]
	v_mfma_f32_16x16x32_bf16 v[66:69], v[182:185], v[214:217], v[66:69]
	v_mfma_f32_16x16x32_bf16 v[118:121], v[178:181], v[194:197], v[118:121]
	v_mfma_f32_16x16x32_bf16 v[114:117], v[186:189], v[194:197], v[114:117]
	v_mfma_f32_16x16x32_bf16 v[102:105], v[178:181], v[202:205], v[102:105]
	v_mfma_f32_16x16x32_bf16 v[98:101], v[186:189], v[202:205], v[98:101]
	v_mfma_f32_16x16x32_bf16 v[86:89], v[178:181], v[210:213], v[86:89]
	v_mfma_f32_16x16x32_bf16 v[82:85], v[186:189], v[210:213], v[82:85]
	v_mfma_f32_16x16x32_bf16 v[70:73], v[178:181], v[218:221], v[70:73]
	v_mfma_f32_16x16x32_bf16 v[66:69], v[186:189], v[218:221], v[66:69]
	s_setprio 0
	s_barrier
; #define PG8_STAGE(bufoff, gbase, voff) do { _Pragma("unroll") for (int _i = 0; _i < 2; ++_i) \
;         __builtin_amdgcn_global_load_lds((const __attribute__((address_space(1))) unsigned*)((const char*)(gbase) + (voff)[_i]), (LAS unsigned*)(lds + (bufoff) + ldsw + _i * 8192), 16, 0, 0); } while (0)
; #define PG8_LDA(dst, b, h) do { _Pragma("unroll") for (int m = 0; m < 4; ++m) _Pragma("unroll") for (int k = 0; k < 2; ++k) dst[m][k] = *(const LAS bf16x8*)(lds + PG8_SA(b, h) + aoff + m * 2048 + k * 1024); } while (0)
; #define PG8_MMA(ai, bj, At, Bt) do { __builtin_amdgcn_s_setprio(1); _Pragma("unroll") for (int m = 0; m < 4; ++m) _Pragma("unroll") for (int n = 0; n < 2; ++n) _Pragma("unroll") for (int k = 0; k < 2; ++k) \
;         acc[ai][bj][m][n] = __builtin_amdgcn_mfma_f32_16x16x32_bf16(Bt[n][k], At[m][k], acc[ai][bj][m][n], 0, 0, 0); __builtin_amdgcn_s_setprio(0); } while (0)
; #define PG8_WAIT_V(n) asm volatile("s_waitcnt vmcnt(" #n ")" ::: "memory")
; #define PG8_WAIT_L(n) asm volatile("s_waitcnt lgkmcnt(" #n ")" ::: "memory")
; #define PG8_BAR __builtin_amdgcn_s_barrier()
; #define PG8_SCHED __builtin_amdgcn_sched_barrier(0)
; template <class Epi, class SchedT, bool ALIGN_EPI, bool SP2>
; __device__ __forceinline__ void gemm_phase(LAS unsigned char* lds, const int ldk, const int nt, const SchedT& S, const Epi& E) {
;     ...
;             PG8_LDA(At, 1, 1); PG8_STAGE(PG8_SB(1, 0), b3, voffB); PG8_STAGE(PG8_SB(1, 1), b3 + hstepB, voffB); PG8_STAGE(PG8_SA(1, 0), a3, voffA);
;             PG8_WAIT_V(8); PG8_WAIT_L(0); PG8_BAR; PG8_MMA(1, 0, At, B0); PG8_MMA(1, 1, At, B1); PG8_BAR; PG8_SCHED;
;     ...
;         if constexpr (ALIGN_EPI) { if (wr == 0) PG8_BAR; }
;     __device__ __forceinline__ void operator()(f32x4 (&acc)[2][2][4][2], const Unit& u, int wr, int wc, int fr, int fq) const {
;     ...
;                 const int row = row0 + ai * HALF + m * 16; float sq = 0.f;
; #pragma unroll
;                 for (int bj = 0; bj < 2; ++bj) {
;                     const size_t off = (size_t)row * D + col0 + bj * 32;
;                     const u32x4 xw = *(const u32x4*)(xin + off);
	s_add_i32 s51, s51, s61
	v_lshl_add_u64 v[144:145], v[144:145], 0, s[24:25]
	s_mov_b32 m0, s51
	ds_read_b128 v[190:193], v149 offset:49152
	ds_read_b128 v[194:197], v149 offset:50176
	ds_read_b128 v[198:201], v149 offset:51200
	ds_read_b128 v[202:205], v149 offset:52224
	ds_read_b128 v[206:209], v149 offset:53248
	ds_read_b128 v[210:213], v149 offset:54272
	ds_read_b128 v[214:217], v149 offset:55296
	ds_read_b128 v[218:221], v149 offset:56320
	global_load_lds_dwordx4 v[144:145], off
	s_add_i32 m0, s51, 0x2000
	s_add_u32 s36, s36, 0x20080
	v_lshl_add_u64 v[144:145], v[222:223], 0, s[24:25]
	s_addc_u32 s37, s37, 0
	s_add_i32 s51, s53, s61
	global_load_lds_dwordx4 v[144:145], off
	v_lshl_add_u64 v[144:145], s[36:37], 0, v[0:1]
	s_mov_b32 m0, s51
	s_nop 0
	global_load_lds_dwordx4 v[144:145], off
	v_lshl_add_u64 v[144:145], s[36:37], 0, v[134:135]
	s_add_i32 m0, s51, 0x2000
	s_nop 0
	global_load_lds_dwordx4 v[144:145], off
	v_lshl_add_u64 v[144:145], v[224:225], 0, s[24:25]
	s_mov_b32 m0, s83
	s_nop 0
	global_load_lds_dwordx4 v[144:145], off
	v_lshl_add_u64 v[144:145], v[226:227], 0, s[24:25]
	s_mov_b32 m0, s84
	s_nop 0
	global_load_lds_dwordx4 v[144:145], off
	s_waitcnt vmcnt(8)
	s_waitcnt lgkmcnt(0)
	s_barrier
	s_setprio 1
	s_waitcnt lgkmcnt(0)
	v_mfma_f32_16x16x32_bf16 v[62:65], v[140:143], v[190:193], v[62:65]
	v_mfma_f32_16x16x32_bf16 v[58:61], v[154:157], v[190:193], v[58:61]
	v_mfma_f32_16x16x32_bf16 v[46:49], v[140:143], v[198:201], v[46:49]
	v_mfma_f32_16x16x32_bf16 v[42:45], v[154:157], v[198:201], v[42:45]
	v_mfma_f32_16x16x32_bf16 v[30:33], v[140:143], v[206:209], v[30:33]
	v_mfma_f32_16x16x32_bf16 v[26:29], v[154:157], v[206:209], v[26:29]
	v_mfma_f32_16x16x32_bf16 v[14:17], v[140:143], v[214:217], v[14:17]
	v_mfma_f32_16x16x32_bf16 v[10:13], v[154:157], v[214:217], v[10:13]
	v_mfma_f32_16x16x32_bf16 v[62:65], v[150:153], v[194:197], v[62:65]
	v_mfma_f32_16x16x32_bf16 v[58:61], v[158:161], v[194:197], v[58:61]
	v_mfma_f32_16x16x32_bf16 v[46:49], v[150:153], v[202:205], v[46:49]
	v_mfma_f32_16x16x32_bf16 v[42:45], v[158:161], v[202:205], v[42:45]
	v_mfma_f32_16x16x32_bf16 v[30:33], v[150:153], v[210:213], v[30:33]
	v_mfma_f32_16x16x32_bf16 v[26:29], v[158:161], v[210:213], v[26:29]
	v_mfma_f32_16x16x32_bf16 v[14:17], v[150:153], v[218:221], v[14:17]
	v_mfma_f32_16x16x32_bf16 v[10:13], v[158:161], v[218:221], v[10:13]
	v_mfma_f32_16x16x32_bf16 v[54:57], v[174:177], v[190:193], v[54:57]
	v_mfma_f32_16x16x32_bf16 v[50:53], v[182:185], v[190:193], v[50:53]
	v_mfma_f32_16x16x32_bf16 v[38:41], v[174:177], v[198:201], v[38:41]
	v_mfma_f32_16x16x32_bf16 v[34:37], v[182:185], v[198:201], v[34:37]
	v_mfma_f32_16x16x32_bf16 v[22:25], v[174:177], v[206:209], v[22:25]
	v_mfma_f32_16x16x32_bf16 v[18:21], v[182:185], v[206:209], v[18:21]
	v_mfma_f32_16x16x32_bf16 v[6:9], v[174:177], v[214:217], v[6:9]
	v_mfma_f32_16x16x32_bf16 v[2:5], v[182:185], v[214:217], v[2:5]
	v_mfma_f32_16x16x32_bf16 v[54:57], v[178:181], v[194:197], v[54:57]
	v_mfma_f32_16x16x32_bf16 v[50:53], v[186:189], v[194:197], v[50:53]
	v_mfma_f32_16x16x32_bf16 v[38:41], v[178:181], v[202:205], v[38:41]
	v_mfma_f32_16x16x32_bf16 v[34:37], v[186:189], v[202:205], v[34:37]
	v_mfma_f32_16x16x32_bf16 v[22:25], v[178:181], v[210:213], v[22:25]
	v_mfma_f32_16x16x32_bf16 v[18:21], v[186:189], v[210:213], v[18:21]
	v_mfma_f32_16x16x32_bf16 v[6:9], v[178:181], v[218:221], v[6:9]
	v_mfma_f32_16x16x32_bf16 v[2:5], v[186:189], v[218:221], v[2:5]
	s_setprio 0
	s_barrier
	s_add_i32 s22, s22, 2
	s_add_u32 s34, s34, 0x100
	s_addc_u32 s35, s35, 0
	s_add_u32 s13, s13, 0x100
	s_addc_u32 s20, s20, 0
	s_cmp_gt_u32 s22, 29
	s_cbranch_scc0 .LBB0_668
	v_lshl_add_u32 v142, s16, 8, v146
	v_lshl_or_b32 v140, s12, 8, v148
	v_lshlrev_b32_e32 v141, 12, v142
	v_lshl_add_u32 v150, v140, 1, v141
	v_add_u32_e32 v151, 0x10000, v150
	v_add_u32_e32 v152, 0x20000, v150
	v_add_u32_e32 v153, 0x30000, v150
	v_add_u32_e32 v154, 0x80000, v150
	v_add_u32_e32 v155, 0x90000, v150
	v_add_u32_e32 v156, 0xa0000, v150
	v_add_u32_e32 v157, 0xb0000, v150
	global_load_dwordx4 v[174:177], v150, s[42:43]
	global_load_dwordx4 v[178:181], v150, s[42:43] offset:64
	global_load_dwordx4 v[182:185], v151, s[42:43]
	global_load_dwordx4 v[186:189], v151, s[42:43] offset:64
	global_load_dwordx4 v[190:193], v152, s[42:43]
	global_load_dwordx4 v[194:197], v152, s[42:43] offset:64
	global_load_dwordx4 v[198:201], v153, s[42:43]
	global_load_dwordx4 v[202:205], v153, s[42:43] offset:64
	global_load_dwordx4 v[206:209], v154, s[42:43]
	global_load_dwordx4 v[210:213], v154, s[42:43] offset:64
	global_load_dwordx4 v[214:217], v155, s[42:43]
	global_load_dwordx4 v[218:221], v155, s[42:43] offset:64
	global_load_dwordx4 v[222:225], v156, s[42:43]
	global_load_dwordx4 v[226:229], v156, s[42:43] offset:64
	global_load_dwordx4 v[230:233], v157, s[42:43]
	global_load_dwordx4 v[234:237], v157, s[42:43] offset:64
	s_lshl_b32 s56, s12, 4
	s_lshl_b32 s22, s82, 2
	s_add_i32 s56, s56, s22
	v_lshl_add_u32 v158, v142, 7, s56
	v_add_u32_e32 v159, 0x1000, v158
	v_add_u32_e32 v160, 0x4000, v158
	v_add_u32_e32 v161, 0x5000, v158
	v_xor_b32_e32 v239, 16, v241
	v_xor_b32_e32 v252, 32, v241
	v_lshlrev_b32_e32 v239, 2, v239
	v_lshlrev_b32_e32 v252, 2, v252
	s_and_b64 vcc, exec, s[48:49]
	s_cbranch_vccz .LBB0_671
	s_barrier
	s_setprio 3

; #define PG8_WAIT_V(n) asm volatile("s_waitcnt vmcnt(" #n ")" ::: "memory")
; #define PG8_BAR __builtin_amdgcn_s_barrier()
; template <class Epi, class SchedT, bool ALIGN_EPI, bool SP2>
; __device__ __forceinline__ void gemm_phase(LAS unsigned char* lds, const int ldk, const int nt, const SchedT& S, const Epi& E) {
;     ...
;     PG8_WAIT_V(0);
;     if constexpr (!ALIGN_EPI) { if (wr == 0) PG8_BAR; }
;     PG8_BAR;
.LBB0_690:
	s_setprio 0
	s_waitcnt vmcnt(0)
	v_readlane_b32 s84, v163, 29
	v_readlane_b32 s60, v163, 31
	v_readlane_b32 s85, v163, 30
	v_readlane_b32 s61, v163, 32
	s_barrier

; #define PG8_STAGE(bufoff, gbase, voff) do { _Pragma("unroll") for (int _i = 0; _i < 2; ++_i) \
;         __builtin_amdgcn_global_load_lds((const __attribute__((address_space(1))) unsigned*)((const char*)(gbase) + (voff)[_i]), (LAS unsigned*)(lds + (bufoff) + ldsw + _i * 8192), 16, 0, 0); } while (0)
; #define PG8_LDA(dst, b, h) do { _Pragma("unroll") for (int m = 0; m < 4; ++m) _Pragma("unroll") for (int k = 0; k < 2; ++k) dst[m][k] = *(const LAS bf16x8*)(lds + PG8_SA(b, h) + aoff + m * 2048 + k * 1024); } while (0)
; #define PG8_LDB(dst, b, h) do { _Pragma("unroll") for (int n = 0; n < 2; ++n) _Pragma("unroll") for (int k = 0; k < 2; ++k) dst[n][k] = *(const LAS bf16x8*)(lds + PG8_SB(b, h) + boff + n * 2048 + k * 1024); } while (0)
; #define PG8_MMA(ai, bj, At, Bt) do { __builtin_amdgcn_s_setprio(1); _Pragma("unroll") for (int m = 0; m < 4; ++m) _Pragma("unroll") for (int n = 0; n < 2; ++n) _Pragma("unroll") for (int k = 0; k < 2; ++k) \
;         acc[ai][bj][m][n] = __builtin_amdgcn_mfma_f32_16x16x32_bf16(Bt[n][k], At[m][k], acc[ai][bj][m][n], 0, 0, 0); __builtin_amdgcn_s_setprio(0); } while (0)
; #define PG8_WAIT_V(n) asm volatile("s_waitcnt vmcnt(" #n ")" ::: "memory")
; #define PG8_WAIT_L(n) asm volatile("s_waitcnt lgkmcnt(" #n ")" ::: "memory")
; #define PG8_BAR __builtin_amdgcn_s_barrier()
; #define PG8_SCHED __builtin_amdgcn_sched_barrier(0)
; template <class Epi, class SchedT, bool ALIGN_EPI, bool SP2>
; __device__ __forceinline__ void gemm_phase(LAS unsigned char* lds, const int ldk, const int nt, const SchedT& S, const Epi& E) {
;     ...
;             const bool last = (t == nt - 2);
;             const char* a1 = cA + (size_t)(t + 1) * kstep;
;             const char* a2 = last ? nA : cA + (size_t)(t + 2) * kstep; const char* b2 = last ? nB : cB + (size_t)(t + 2) * kstep;
;             const char* a3 = a2 + kstep; const char* b3 = b2 + kstep;
;             if constexpr (SP2) {
;             PG8_LDB(B0, 0, 0); PG8_LDB(B1, 0, 1); PG8_SCHED; PG8_LDA(At, 0, 0); PG8_STAGE(PG8_SA(1, 1), a1 + hstep, voffA);
;             PG8_WAIT_V(8); PG8_WAIT_L(0); PG8_BAR; PG8_MMA(0, 0, At, B0); PG8_MMA(0, 1, At, B1); PG8_BAR; PG8_SCHED;
;             PG8_LDA(At, 0, 1); PG8_STAGE(PG8_SB(0, 0), b2, voffB); PG8_STAGE(PG8_SB(0, 1), b2 + hstepB, voffB); PG8_STAGE(PG8_SA(0, 0), a2, voffA);
.LBB0_752:
	s_add_u32 s36, s34, 0xfff80080
	s_addc_u32 s37, s35, -1
	s_add_i32 s61, 0, 0x10000
	s_cmp_eq_u32 s59, 28
	s_cselect_b32 vcc_hi, s1, s37
	s_cselect_b32 vcc_lo, s0, s36
	s_cselect_b32 s37, s63, s17
	s_cselect_b32 s36, s62, s13
	s_add_i32 s64, 0, 0x14000
	v_add_u32_e32 v142, s61, v248
	v_add_u32_e32 v182, s64, v248
	ds_read_b128 v[130:133], v142
	ds_read_b128 v[134:137], v142 offset:1024
	ds_read_b128 v[138:141], v142 offset:2048
	ds_read_b128 v[142:145], v142 offset:3072
	ds_read_b128 v[158:161], v182
	ds_read_b128 v[174:177], v182 offset:1024
	ds_read_b128 v[178:181], v182 offset:2048
	ds_read_b128 v[182:185], v182 offset:3072
	v_lshl_add_u64 v[218:219], s[34:35], 0, v[154:155]
	s_add_i32 m0, s85, 0xc000
	ds_read_b128 v[186:189], v251
	ds_read_b128 v[190:193], v251 offset:1024
	ds_read_b128 v[194:197], v251 offset:2048
	ds_read_b128 v[198:201], v251 offset:3072
	ds_read_b128 v[202:205], v251 offset:4096
	ds_read_b128 v[206:209], v251 offset:5120
	ds_read_b128 v[210:213], v251 offset:6144
	ds_read_b128 v[214:217], v251 offset:7168
	global_load_lds_dwordx4 v[218:219], off
	v_lshl_add_u64 v[218:219], s[34:35], 0, v[156:157]
	s_add_i32 m0, s85, 0xe000
	s_nop 0
	global_load_lds_dwordx4 v[218:219], off
	s_waitcnt vmcnt(8)
	s_waitcnt lgkmcnt(0)
	s_barrier
	s_setprio 1
	s_waitcnt lgkmcnt(0)
	v_mfma_f32_16x16x32_bf16 v[126:129], v[130:133], v[186:189], v[126:129]
	v_mfma_f32_16x16x32_bf16 v[62:65], v[138:141], v[186:189], v[62:65]
	v_mfma_f32_16x16x32_bf16 v[118:121], v[130:133], v[194:197], v[118:121]
	v_mfma_f32_16x16x32_bf16 v[58:61], v[138:141], v[194:197], v[58:61]
	v_mfma_f32_16x16x32_bf16 v[110:113], v[130:133], v[202:205], v[110:113]
	v_mfma_f32_16x16x32_bf16 v[46:49], v[138:141], v[202:205], v[46:49]
	v_mfma_f32_16x16x32_bf16 v[106:109], v[130:133], v[210:213], v[106:109]
	v_mfma_f32_16x16x32_bf16 v[42:45], v[138:141], v[210:213], v[42:45]
	v_mfma_f32_16x16x32_bf16 v[126:129], v[134:137], v[190:193], v[126:129]
	v_mfma_f32_16x16x32_bf16 v[62:65], v[142:145], v[190:193], v[62:65]
	v_mfma_f32_16x16x32_bf16 v[118:121], v[134:137], v[198:201], v[118:121]
	v_mfma_f32_16x16x32_bf16 v[58:61], v[142:145], v[198:201], v[58:61]
	v_mfma_f32_16x16x32_bf16 v[110:113], v[134:137], v[206:209], v[110:113]
	v_mfma_f32_16x16x32_bf16 v[46:49], v[142:145], v[206:209], v[46:49]
	v_mfma_f32_16x16x32_bf16 v[106:109], v[134:137], v[214:217], v[106:109]
	v_mfma_f32_16x16x32_bf16 v[42:45], v[142:145], v[214:217], v[42:45]
	v_mfma_f32_16x16x32_bf16 v[122:125], v[158:161], v[186:189], v[122:125]
	v_mfma_f32_16x16x32_bf16 v[54:57], v[178:181], v[186:189], v[54:57]
	v_mfma_f32_16x16x32_bf16 v[114:117], v[158:161], v[194:197], v[114:117]
	v_mfma_f32_16x16x32_bf16 v[50:53], v[178:181], v[194:197], v[50:53]
	v_mfma_f32_16x16x32_bf16 v[102:105], v[158:161], v[202:205], v[102:105]
	v_mfma_f32_16x16x32_bf16 v[38:41], v[178:181], v[202:205], v[38:41]
	v_mfma_f32_16x16x32_bf16 v[98:101], v[158:161], v[210:213], v[98:101]
	v_mfma_f32_16x16x32_bf16 v[34:37], v[178:181], v[210:213], v[34:37]
	v_mfma_f32_16x16x32_bf16 v[122:125], v[174:177], v[190:193], v[122:125]
	v_mfma_f32_16x16x32_bf16 v[54:57], v[182:185], v[190:193], v[54:57]
	v_mfma_f32_16x16x32_bf16 v[114:117], v[174:177], v[198:201], v[114:117]
	v_mfma_f32_16x16x32_bf16 v[50:53], v[182:185], v[198:201], v[50:53]
	v_mfma_f32_16x16x32_bf16 v[102:105], v[174:177], v[206:209], v[102:105]
	v_mfma_f32_16x16x32_bf16 v[38:41], v[182:185], v[206:209], v[38:41]
	v_mfma_f32_16x16x32_bf16 v[98:101], v[174:177], v[214:217], v[98:101]
	v_mfma_f32_16x16x32_bf16 v[34:37], v[182:185], v[214:217], v[34:37]
	s_setprio 0
	s_barrier
	s_add_i32 s61, s61, s84
	v_lshl_add_u64 v[218:219], s[36:37], 0, v[0:1]
	s_mov_b32 m0, s61
	ds_read_b128 v[186:189], v251 offset:16384
	ds_read_b128 v[190:193], v251 offset:17408
	ds_read_b128 v[194:197], v251 offset:18432
	ds_read_b128 v[198:201], v251 offset:19456
	ds_read_b128 v[202:205], v251 offset:20480
	ds_read_b128 v[206:209], v251 offset:21504
	ds_read_b128 v[210:213], v251 offset:22528
	ds_read_b128 v[214:217], v251 offset:23552
	global_load_lds_dwordx4 v[218:219], off
	s_add_i32 m0, s61, 0x2000
	s_add_u32 s94, s36, 0x20000
	v_lshl_add_u64 v[220:221], s[36:37], 0, v[150:151]
	s_addc_u32 s95, s37, 0
	s_add_i32 s61, s64, s84
	global_load_lds_dwordx4 v[220:221], off
	v_lshl_add_u64 v[222:223], s[94:95], 0, v[0:1]
	s_mov_b32 m0, s61
	v_lshl_add_u64 v[224:225], vcc, 0, v[148:149]
	global_load_lds_dwordx4 v[222:223], off
	v_lshl_add_u64 v[222:223], s[94:95], 0, v[150:151]
	s_add_i32 m0, s61, 0x2000
	s_nop 0
	global_load_lds_dwordx4 v[222:223], off
	v_lshl_add_u64 v[222:223], vcc, 0, v[146:147]
	s_mov_b32 m0, s85
	s_nop 0
	global_load_lds_dwordx4 v[222:223], off
	s_mov_b32 m0, s86
	s_nop 0
	global_load_lds_dwordx4 v[224:225], off
	s_waitcnt vmcnt(8)
	s_waitcnt lgkmcnt(0)
	s_barrier
; #define PG8_STAGE(bufoff, gbase, voff) do { _Pragma("unroll") for (int _i = 0; _i < 2; ++_i) \
;         __builtin_amdgcn_global_load_lds((const __attribute__((address_space(1))) unsigned*)((const char*)(gbase) + (voff)[_i]), (LAS unsigned*)(lds + (bufoff) + ldsw + _i * 8192), 16, 0, 0); } while (0)
; #define PG8_LDA(dst, b, h) do { _Pragma("unroll") for (int m = 0; m < 4; ++m) _Pragma("unroll") for (int k = 0; k < 2; ++k) dst[m][k] = *(const LAS bf16x8*)(lds + PG8_SA(b, h) + aoff + m * 2048 + k * 1024); } while (0)
; #define PG8_LDB(dst, b, h) do { _Pragma("unroll") for (int n = 0; n < 2; ++n) _Pragma("unroll") for (int k = 0; k < 2; ++k) dst[n][k] = *(const LAS bf16x8*)(lds + PG8_SB(b, h) + boff + n * 2048 + k * 1024); } while (0)
; #define PG8_MMA(ai, bj, At, Bt) do { __builtin_amdgcn_s_setprio(1); _Pragma("unroll") for (int m = 0; m < 4; ++m) _Pragma("unroll") for (int n = 0; n < 2; ++n) _Pragma("unroll") for (int k = 0; k < 2; ++k) \
;         acc[ai][bj][m][n] = __builtin_amdgcn_mfma_f32_16x16x32_bf16(Bt[n][k], At[m][k], acc[ai][bj][m][n], 0, 0, 0); __builtin_amdgcn_s_setprio(0); } while (0)
; #define PG8_WAIT_V(n) asm volatile("s_waitcnt vmcnt(" #n ")" ::: "memory")
; #define PG8_WAIT_L(n) asm volatile("s_waitcnt lgkmcnt(" #n ")" ::: "memory")
; #define PG8_BAR __builtin_amdgcn_s_barrier()
; #define PG8_SCHED __builtin_amdgcn_sched_barrier(0)
; template <class Epi, class SchedT, bool ALIGN_EPI, bool SP2>
; __device__ __forceinline__ void gemm_phase(LAS unsigned char* lds, const int ldk, const int nt, const SchedT& S, const Epi& E) {
;     ...
;             PG8_WAIT_V(8); PG8_WAIT_L(0); PG8_BAR; PG8_MMA(1, 0, At, B0); PG8_MMA(1, 1, At, B1); PG8_BAR; PG8_SCHED;
;             PG8_LDB(B0, 1, 0); PG8_LDB(B1, 1, 1); PG8_SCHED; PG8_LDA(At, 1, 0); PG8_STAGE(PG8_SA(0, 1), a2 + hstep, voffA);
;             PG8_WAIT_V(8); PG8_WAIT_L(0); PG8_BAR; PG8_MMA(0, 0, At, B0); PG8_MMA(0, 1, At, B1); PG8_BAR; PG8_SCHED;
	s_setprio 1
	s_waitcnt lgkmcnt(0)
	v_mfma_f32_16x16x32_bf16 v[94:97], v[130:133], v[186:189], v[94:97]
	v_mfma_f32_16x16x32_bf16 v[30:33], v[138:141], v[186:189], v[30:33]
	v_mfma_f32_16x16x32_bf16 v[90:93], v[130:133], v[194:197], v[90:93]
	v_mfma_f32_16x16x32_bf16 v[26:29], v[138:141], v[194:197], v[26:29]
	v_mfma_f32_16x16x32_bf16 v[78:81], v[130:133], v[202:205], v[78:81]
	v_mfma_f32_16x16x32_bf16 v[14:17], v[138:141], v[202:205], v[14:17]
	v_mfma_f32_16x16x32_bf16 v[74:77], v[130:133], v[210:213], v[74:77]
	v_mfma_f32_16x16x32_bf16 v[10:13], v[138:141], v[210:213], v[10:13]
	v_mfma_f32_16x16x32_bf16 v[94:97], v[134:137], v[190:193], v[94:97]
	v_mfma_f32_16x16x32_bf16 v[30:33], v[142:145], v[190:193], v[30:33]
	v_mfma_f32_16x16x32_bf16 v[90:93], v[134:137], v[198:201], v[90:93]
	v_mfma_f32_16x16x32_bf16 v[26:29], v[142:145], v[198:201], v[26:29]
	v_mfma_f32_16x16x32_bf16 v[78:81], v[134:137], v[206:209], v[78:81]
	v_mfma_f32_16x16x32_bf16 v[14:17], v[142:145], v[206:209], v[14:17]
	v_mfma_f32_16x16x32_bf16 v[74:77], v[134:137], v[214:217], v[74:77]
	v_mfma_f32_16x16x32_bf16 v[10:13], v[142:145], v[214:217], v[10:13]
	v_mfma_f32_16x16x32_bf16 v[86:89], v[158:161], v[186:189], v[86:89]
	v_mfma_f32_16x16x32_bf16 v[22:25], v[178:181], v[186:189], v[22:25]
	v_mfma_f32_16x16x32_bf16 v[82:85], v[158:161], v[194:197], v[82:85]
	v_mfma_f32_16x16x32_bf16 v[18:21], v[178:181], v[194:197], v[18:21]
	v_mfma_f32_16x16x32_bf16 v[70:73], v[158:161], v[202:205], v[70:73]
	v_mfma_f32_16x16x32_bf16 v[6:9], v[178:181], v[202:205], v[6:9]
	v_mfma_f32_16x16x32_bf16 v[66:69], v[158:161], v[210:213], v[66:69]
	v_mfma_f32_16x16x32_bf16 v[2:5], v[178:181], v[210:213], v[2:5]
	v_mfma_f32_16x16x32_bf16 v[86:89], v[174:177], v[190:193], v[86:89]
	v_mfma_f32_16x16x32_bf16 v[22:25], v[182:185], v[190:193], v[22:25]
	v_mfma_f32_16x16x32_bf16 v[82:85], v[174:177], v[198:201], v[82:85]
	v_mfma_f32_16x16x32_bf16 v[18:21], v[182:185], v[198:201], v[18:21]
	v_mfma_f32_16x16x32_bf16 v[70:73], v[174:177], v[206:209], v[70:73]
	v_mfma_f32_16x16x32_bf16 v[6:9], v[182:185], v[206:209], v[6:9]
	v_mfma_f32_16x16x32_bf16 v[66:69], v[174:177], v[214:217], v[66:69]
	v_mfma_f32_16x16x32_bf16 v[2:5], v[182:185], v[214:217], v[2:5]
	s_setprio 0
	s_barrier
	s_add_i32 s61, 0, 0x18000
	s_add_i32 s64, 0, 0x1c000
	v_add_u32_e32 v142, s61, v248
	v_add_u32_e32 v182, s64, v248
	ds_read_b128 v[130:133], v142
	ds_read_b128 v[134:137], v142 offset:1024
	ds_read_b128 v[138:141], v142 offset:2048
	ds_read_b128 v[142:145], v142 offset:3072
	ds_read_b128 v[158:161], v182
	ds_read_b128 v[174:177], v182 offset:1024
	ds_read_b128 v[178:181], v182 offset:2048
	ds_read_b128 v[182:185], v182 offset:3072
	s_add_u32 s94, vcc_lo, 0x80000
	s_addc_u32 s95, vcc_hi, 0
	s_mov_b32 m0, s87
	v_lshl_add_u64 v[226:227], s[94:95], 0, v[146:147]
	ds_read_b128 v[186:189], v251 offset:32768
	ds_read_b128 v[190:193], v251 offset:33792
	ds_read_b128 v[194:197], v251 offset:34816
	ds_read_b128 v[198:201], v251 offset:35840
	ds_read_b128 v[202:205], v251 offset:36864
	ds_read_b128 v[206:209], v251 offset:37888
	ds_read_b128 v[210:213], v251 offset:38912
	ds_read_b128 v[214:217], v251 offset:39936
	global_load_lds_dwordx4 v[226:227], off
	v_lshl_add_u64 v[226:227], s[94:95], 0, v[148:149]
	s_mov_b32 m0, s88
	s_nop 0
	global_load_lds_dwordx4 v[226:227], off
	s_waitcnt vmcnt(8)
	s_waitcnt lgkmcnt(0)
	s_barrier
	s_setprio 1
	s_waitcnt lgkmcnt(0)
	v_mfma_f32_16x16x32_bf16 v[126:129], v[130:133], v[186:189], v[126:129]
	v_mfma_f32_16x16x32_bf16 v[62:65], v[138:141], v[186:189], v[62:65]
	v_mfma_f32_16x16x32_bf16 v[118:121], v[130:133], v[194:197], v[118:121]
	v_mfma_f32_16x16x32_bf16 v[58:61], v[138:141], v[194:197], v[58:61]
	v_mfma_f32_16x16x32_bf16 v[110:113], v[130:133], v[202:205], v[110:113]
	v_mfma_f32_16x16x32_bf16 v[46:49], v[138:141], v[202:205], v[46:49]
	v_mfma_f32_16x16x32_bf16 v[106:109], v[130:133], v[210:213], v[106:109]
	v_mfma_f32_16x16x32_bf16 v[42:45], v[138:141], v[210:213], v[42:45]
	v_mfma_f32_16x16x32_bf16 v[126:129], v[134:137], v[190:193], v[126:129]
	v_mfma_f32_16x16x32_bf16 v[62:65], v[142:145], v[190:193], v[62:65]
	v_mfma_f32_16x16x32_bf16 v[118:121], v[134:137], v[198:201], v[118:121]
	v_mfma_f32_16x16x32_bf16 v[58:61], v[142:145], v[198:201], v[58:61]
	v_mfma_f32_16x16x32_bf16 v[110:113], v[134:137], v[206:209], v[110:113]
	v_mfma_f32_16x16x32_bf16 v[46:49], v[142:145], v[206:209], v[46:49]
	v_mfma_f32_16x16x32_bf16 v[106:109], v[134:137], v[214:217], v[106:109]
	v_mfma_f32_16x16x32_bf16 v[42:45], v[142:145], v[214:217], v[42:45]
	v_mfma_f32_16x16x32_bf16 v[122:125], v[158:161], v[186:189], v[122:125]
	v_mfma_f32_16x16x32_bf16 v[54:57], v[178:181], v[186:189], v[54:57]
	v_mfma_f32_16x16x32_bf16 v[114:117], v[158:161], v[194:197], v[114:117]
	v_mfma_f32_16x16x32_bf16 v[50:53], v[178:181], v[194:197], v[50:53]
	v_mfma_f32_16x16x32_bf16 v[102:105], v[158:161], v[202:205], v[102:105]
	v_mfma_f32_16x16x32_bf16 v[38:41], v[178:181], v[202:205], v[38:41]
	v_mfma_f32_16x16x32_bf16 v[98:101], v[158:161], v[210:213], v[98:101]
	v_mfma_f32_16x16x32_bf16 v[34:37], v[178:181], v[210:213], v[34:37]
	v_mfma_f32_16x16x32_bf16 v[122:125], v[174:177], v[190:193], v[122:125]
	v_mfma_f32_16x16x32_bf16 v[54:57], v[182:185], v[190:193], v[54:57]
	v_mfma_f32_16x16x32_bf16 v[114:117], v[174:177], v[198:201], v[114:117]
	v_mfma_f32_16x16x32_bf16 v[50:53], v[182:185], v[198:201], v[50:53]
	v_mfma_f32_16x16x32_bf16 v[102:105], v[174:177], v[206:209], v[102:105]
	v_mfma_f32_16x16x32_bf16 v[38:41], v[182:185], v[206:209], v[38:41]
	v_mfma_f32_16x16x32_bf16 v[98:101], v[174:177], v[214:217], v[98:101]
	v_mfma_f32_16x16x32_bf16 v[34:37], v[182:185], v[214:217], v[34:37]
	s_setprio 0
	s_barrier
; #define PG8_STAGE(bufoff, gbase, voff) do { _Pragma("unroll") for (int _i = 0; _i < 2; ++_i) \
;         __builtin_amdgcn_global_load_lds((const __attribute__((address_space(1))) unsigned*)((const char*)(gbase) + (voff)[_i]), (LAS unsigned*)(lds + (bufoff) + ldsw + _i * 8192), 16, 0, 0); } while (0)
; #define PG8_LDA(dst, b, h) do { _Pragma("unroll") for (int m = 0; m < 4; ++m) _Pragma("unroll") for (int k = 0; k < 2; ++k) dst[m][k] = *(const LAS bf16x8*)(lds + PG8_SA(b, h) + aoff + m * 2048 + k * 1024); } while (0)
; #define PG8_MMA(ai, bj, At, Bt) do { __builtin_amdgcn_s_setprio(1); _Pragma("unroll") for (int m = 0; m < 4; ++m) _Pragma("unroll") for (int n = 0; n < 2; ++n) _Pragma("unroll") for (int k = 0; k < 2; ++k) \
;         acc[ai][bj][m][n] = __builtin_amdgcn_mfma_f32_16x16x32_bf16(Bt[n][k], At[m][k], acc[ai][bj][m][n], 0, 0, 0); __builtin_amdgcn_s_setprio(0); } while (0)
; #define PG8_WAIT_V(n) asm volatile("s_waitcnt vmcnt(" #n ")" ::: "memory")
; #define PG8_WAIT_L(n) asm volatile("s_waitcnt lgkmcnt(" #n ")" ::: "memory")
; #define PG8_BAR __builtin_amdgcn_s_barrier()
; #define PG8_SCHED __builtin_amdgcn_sched_barrier(0)
; __device__ __forceinline__ float row_rstd(const float* ssp, int row, int fq) {
;     const f32x4 a = *(const f32x4*)(ssp + (size_t)row * 32 + 8 * fq), b = *(const f32x4*)(ssp + (size_t)row * 32 + 8 * fq + 4);
; template <class Epi, class SchedT, bool ALIGN_EPI, bool SP2>
; __device__ __forceinline__ void gemm_phase(LAS unsigned char* lds, const int ldk, const int nt, const SchedT& S, const Epi& E) {
;     ...
;             PG8_LDA(At, 1, 1); PG8_STAGE(PG8_SB(1, 0), b3, voffB); PG8_STAGE(PG8_SB(1, 1), b3 + hstepB, voffB); PG8_STAGE(PG8_SA(1, 0), a3, voffA);
;             PG8_WAIT_V(8); PG8_WAIT_L(0); PG8_BAR; PG8_MMA(1, 0, At, B0); PG8_MMA(1, 1, At, B1); PG8_BAR; PG8_SCHED;
;     ...
;         if constexpr (ALIGN_EPI) { if (wr == 0) PG8_BAR; }
	s_add_i32 s61, s61, s84
	v_lshl_add_u64 v[218:219], v[218:219], 0, s[24:25]
	s_mov_b32 m0, s61
	ds_read_b128 v[186:189], v251 offset:49152
	ds_read_b128 v[190:193], v251 offset:50176
	ds_read_b128 v[194:197], v251 offset:51200
	ds_read_b128 v[198:201], v251 offset:52224
	ds_read_b128 v[202:205], v251 offset:53248
	ds_read_b128 v[206:209], v251 offset:54272
	ds_read_b128 v[210:213], v251 offset:55296
	ds_read_b128 v[214:217], v251 offset:56320
	global_load_lds_dwordx4 v[218:219], off
	s_add_i32 m0, s61, 0x2000
	s_add_u32 s36, s36, 0x20080
	v_lshl_add_u64 v[218:219], v[220:221], 0, s[24:25]
	s_addc_u32 s37, s37, 0
	s_add_i32 s61, s64, s84
	global_load_lds_dwordx4 v[218:219], off
	v_lshl_add_u64 v[218:219], s[36:37], 0, v[0:1]
	s_mov_b32 m0, s61
	s_nop 0
	global_load_lds_dwordx4 v[218:219], off
	v_lshl_add_u64 v[218:219], s[36:37], 0, v[150:151]
	s_add_i32 m0, s61, 0x2000
	s_nop 0
	global_load_lds_dwordx4 v[218:219], off
	v_lshl_add_u64 v[218:219], v[222:223], 0, s[24:25]
	s_mov_b32 m0, s89
	s_nop 0
	global_load_lds_dwordx4 v[218:219], off
	v_lshl_add_u64 v[218:219], v[224:225], 0, s[24:25]
	s_mov_b32 m0, s90
	s_nop 0
	global_load_lds_dwordx4 v[218:219], off
	s_waitcnt vmcnt(8)
	s_waitcnt lgkmcnt(0)
	s_barrier
	s_setprio 1
	s_waitcnt lgkmcnt(0)
	v_mfma_f32_16x16x32_bf16 v[94:97], v[130:133], v[186:189], v[94:97]
	v_mfma_f32_16x16x32_bf16 v[30:33], v[138:141], v[186:189], v[30:33]
	v_mfma_f32_16x16x32_bf16 v[90:93], v[130:133], v[194:197], v[90:93]
	v_mfma_f32_16x16x32_bf16 v[26:29], v[138:141], v[194:197], v[26:29]
	v_mfma_f32_16x16x32_bf16 v[78:81], v[130:133], v[202:205], v[78:81]
	v_mfma_f32_16x16x32_bf16 v[14:17], v[138:141], v[202:205], v[14:17]
	v_mfma_f32_16x16x32_bf16 v[74:77], v[130:133], v[210:213], v[74:77]
	v_mfma_f32_16x16x32_bf16 v[10:13], v[138:141], v[210:213], v[10:13]
	v_mfma_f32_16x16x32_bf16 v[94:97], v[134:137], v[190:193], v[94:97]
	v_mfma_f32_16x16x32_bf16 v[30:33], v[142:145], v[190:193], v[30:33]
	v_mfma_f32_16x16x32_bf16 v[90:93], v[134:137], v[198:201], v[90:93]
	v_mfma_f32_16x16x32_bf16 v[26:29], v[142:145], v[198:201], v[26:29]
	v_mfma_f32_16x16x32_bf16 v[78:81], v[134:137], v[206:209], v[78:81]
	v_mfma_f32_16x16x32_bf16 v[14:17], v[142:145], v[206:209], v[14:17]
	v_mfma_f32_16x16x32_bf16 v[74:77], v[134:137], v[214:217], v[74:77]
	v_mfma_f32_16x16x32_bf16 v[10:13], v[142:145], v[214:217], v[10:13]
	v_mfma_f32_16x16x32_bf16 v[86:89], v[158:161], v[186:189], v[86:89]
	v_mfma_f32_16x16x32_bf16 v[22:25], v[178:181], v[186:189], v[22:25]
	v_mfma_f32_16x16x32_bf16 v[82:85], v[158:161], v[194:197], v[82:85]
	v_mfma_f32_16x16x32_bf16 v[18:21], v[178:181], v[194:197], v[18:21]
	v_mfma_f32_16x16x32_bf16 v[70:73], v[158:161], v[202:205], v[70:73]
	v_mfma_f32_16x16x32_bf16 v[6:9], v[178:181], v[202:205], v[6:9]
	v_mfma_f32_16x16x32_bf16 v[66:69], v[158:161], v[210:213], v[66:69]
	v_mfma_f32_16x16x32_bf16 v[2:5], v[178:181], v[210:213], v[2:5]
	v_mfma_f32_16x16x32_bf16 v[86:89], v[174:177], v[190:193], v[86:89]
	v_mfma_f32_16x16x32_bf16 v[22:25], v[182:185], v[190:193], v[22:25]
	v_mfma_f32_16x16x32_bf16 v[82:85], v[174:177], v[198:201], v[82:85]
	v_mfma_f32_16x16x32_bf16 v[18:21], v[182:185], v[198:201], v[18:21]
	v_mfma_f32_16x16x32_bf16 v[70:73], v[174:177], v[206:209], v[70:73]
	v_mfma_f32_16x16x32_bf16 v[6:9], v[182:185], v[206:209], v[6:9]
	v_mfma_f32_16x16x32_bf16 v[66:69], v[174:177], v[214:217], v[66:69]
	v_mfma_f32_16x16x32_bf16 v[2:5], v[182:185], v[214:217], v[2:5]
	s_setprio 0
	s_barrier
	s_add_i32 s59, s59, 2
	s_add_u32 s34, s34, 0x100
	s_addc_u32 s35, s35, 0
	s_add_u32 s13, s13, 0x100
	s_addc_u32 s17, s17, 0
	s_cmp_gt_u32 s59, 29
	s_cbranch_scc0 .LBB0_752
	v_lshl_add_u32 v130, s12, 8, v247
	v_lshlrev_b32_e32 v140, 7, v130
	v_mov_b32_e32 v141, 0
	v_lshl_add_u64 v[132:133], v[152:153], 0, v[140:141]
	v_add_u32_e32 v140, 0x1000, v140
	v_lshl_add_u64 v[134:135], v[152:153], 0, v[140:141]
	v_add_u32_e32 v140, 0x3000, v140
	v_lshl_add_u64 v[136:137], v[152:153], 0, v[140:141]
	v_add_u32_e32 v140, 0x1000, v140
	v_lshl_add_u64 v[138:139], v[152:153], 0, v[140:141]
	global_load_dwordx4 v[174:177], v[132:133], off
	global_load_dwordx4 v[178:181], v[132:133], off offset:16
	global_load_dwordx4 v[182:185], v[132:133], off offset:2048
	global_load_dwordx4 v[186:189], v[132:133], off offset:2064
	global_load_dwordx4 v[190:193], v[134:135], off
	global_load_dwordx4 v[194:197], v[134:135], off offset:16
	global_load_dwordx4 v[198:201], v[134:135], off offset:2048
	global_load_dwordx4 v[202:205], v[134:135], off offset:2064
	global_load_dwordx4 v[206:209], v[136:137], off
	global_load_dwordx4 v[210:213], v[136:137], off offset:16
	global_load_dwordx4 v[214:217], v[136:137], off offset:2048
	global_load_dwordx4 v[218:221], v[136:137], off offset:2064
	global_load_dwordx4 v[222:225], v[138:139], off
	global_load_dwordx4 v[226:229], v[138:139], off offset:16
	global_load_dwordx4 v[230:233], v[138:139], off offset:2048
	global_load_dwordx4 v[234:237], v[138:139], off offset:2064
	v_xor_b32_e32 v238, 16, v241
	v_xor_b32_e32 v239, 32, v241
	v_lshlrev_b32_e32 v238, 2, v238
	v_lshlrev_b32_e32 v239, 2, v239
	s_and_b64 vcc, exec, s[56:57]
	s_cbranch_vccz .LBB0_755
	s_barrier
	s_setprio 3

; #define PG8_WAIT_V(n) asm volatile("s_waitcnt vmcnt(" #n ")" ::: "memory")
; #define PG8_BAR __builtin_amdgcn_s_barrier()
; template <class Epi, class SchedT, bool ALIGN_EPI, bool SP2>
; __device__ __forceinline__ void gemm_phase(LAS unsigned char* lds, const int ldk, const int nt, const SchedT& S, const Epi& E) {
;     ...
;     PG8_WAIT_V(0);
;     if constexpr (!ALIGN_EPI) { if (wr == 0) PG8_BAR; }
;     PG8_BAR;
.LBB0_790:
	s_setprio 0
	s_waitcnt vmcnt(0)
	v_readlane_b32 s88, v163, 21
	v_readlane_b32 s90, v163, 27
	v_readlane_b32 s84, v163, 29
	v_readlane_b32 s60, v163, 31
	v_readlane_b32 s89, v163, 22
	v_readlane_b32 s80, v163, 23
	v_readlane_b32 s91, v163, 28
	v_readlane_b32 s85, v163, 30
	v_readlane_b32 s61, v163, 32
	v_readlane_b32 s92, v163, 33
	s_mov_b32 s86, 0x20000
	s_mov_b32 s87, 0x28000
	v_mov_b32_e32 v242, v162
	s_barrier
	v_readlane_b32 s81, v163, 24

; #define PG8_STAGE(bufoff, gbase, voff) do { _Pragma("unroll") for (int _i = 0; _i < 2; ++_i) \
;         __builtin_amdgcn_global_load_lds((const __attribute__((address_space(1))) unsigned*)((const char*)(gbase) + (voff)[_i]), (LAS unsigned*)(lds + (bufoff) + ldsw + _i * 8192), 16, 0, 0); } while (0)
; #define PG8_LDA(dst, b, h) do { _Pragma("unroll") for (int m = 0; m < 4; ++m) _Pragma("unroll") for (int k = 0; k < 2; ++k) dst[m][k] = *(const LAS bf16x8*)(lds + PG8_SA(b, h) + aoff + m * 2048 + k * 1024); } while (0)
; #define PG8_LDB(dst, b, h) do { _Pragma("unroll") for (int n = 0; n < 2; ++n) _Pragma("unroll") for (int k = 0; k < 2; ++k) dst[n][k] = *(const LAS bf16x8*)(lds + PG8_SB(b, h) + boff + n * 2048 + k * 1024); } while (0)
; #define PG8_MMA(ai, bj, At, Bt) do { __builtin_amdgcn_s_setprio(1); _Pragma("unroll") for (int m = 0; m < 4; ++m) _Pragma("unroll") for (int n = 0; n < 2; ++n) _Pragma("unroll") for (int k = 0; k < 2; ++k) \
;         acc[ai][bj][m][n] = __builtin_amdgcn_mfma_f32_16x16x32_bf16(Bt[n][k], At[m][k], acc[ai][bj][m][n], 0, 0, 0); __builtin_amdgcn_s_setprio(0); } while (0)
; #define PG8_WAIT_V(n) asm volatile("s_waitcnt vmcnt(" #n ")" ::: "memory")
; #define PG8_WAIT_L(n) asm volatile("s_waitcnt lgkmcnt(" #n ")" ::: "memory")
; #define PG8_BAR __builtin_amdgcn_s_barrier()
; #define PG8_SCHED __builtin_amdgcn_sched_barrier(0)
; template <class Epi, class SchedT, bool ALIGN_EPI, bool SP2>
; __device__ __forceinline__ void gemm_phase(LAS unsigned char* lds, const int ldk, const int nt, const SchedT& S, const Epi& E) {
;     ...
;             const bool last = (t == nt - 2);
;             const char* a1 = cA + (size_t)(t + 1) * kstep;
;             const char* a2 = last ? nA : cA + (size_t)(t + 2) * kstep; const char* b2 = last ? nB : cB + (size_t)(t + 2) * kstep;
;             const char* a3 = a2 + kstep; const char* b3 = b2 + kstep;
;             if constexpr (SP2) {
;             PG8_LDB(B0, 0, 0); PG8_LDB(B1, 0, 1); PG8_SCHED; PG8_LDA(At, 0, 0); PG8_STAGE(PG8_SA(1, 1), a1 + hstep, voffA);
;             PG8_WAIT_V(8); PG8_WAIT_L(0); PG8_BAR; PG8_MMA(0, 0, At, B0); PG8_MMA(0, 1, At, B1); PG8_BAR; PG8_SCHED;
;             PG8_LDA(At, 0, 1); PG8_STAGE(PG8_SB(0, 0), b2, voffB); PG8_STAGE(PG8_SB(0, 1), b2 + hstepB, voffB); PG8_STAGE(PG8_SA(0, 0), a2, voffA);
.LBB0_948:
	s_add_u32 s16, s12, 0x100
	s_addc_u32 s17, s13, 0
	s_add_i32 s64, 0, 0x10000
	s_cmpk_eq_i32 s83, 0x52
	s_cselect_b32 s47, s1, s17
	s_cselect_b32 s46, s0, s16
	v_add_u32_e32 v144, s64, v147
	s_cselect_b32 s45, s43, s82
	s_cselect_b32 s44, s42, s81
	s_add_i32 s65, 0, 0x14000
	ds_read_b128 v[140:143], v144
	ds_read_b128 v[150:153], v144 offset:1024
	ds_read_b128 v[154:157], v144 offset:2048
	ds_read_b128 v[158:161], v144 offset:3072
	v_add_u32_e32 v144, s65, v147
	ds_read_b128 v[174:177], v144
	ds_read_b128 v[178:181], v144 offset:1024
	ds_read_b128 v[182:185], v144 offset:2048
	ds_read_b128 v[186:189], v144 offset:3072
	v_lshl_add_u64 v[144:145], s[12:13], 0, v[136:137]
	s_add_i32 m0, s53, 0xc000
	ds_read_b128 v[190:193], v149
	ds_read_b128 v[194:197], v149 offset:1024
	ds_read_b128 v[198:201], v149 offset:2048
	ds_read_b128 v[202:205], v149 offset:3072
	ds_read_b128 v[206:209], v149 offset:4096
	ds_read_b128 v[210:213], v149 offset:5120
	ds_read_b128 v[214:217], v149 offset:6144
	ds_read_b128 v[218:221], v149 offset:7168
	global_load_lds_dwordx4 v[144:145], off
	v_lshl_add_u64 v[144:145], s[12:13], 0, v[138:139]
	s_add_i32 m0, s53, 0xe000
	s_nop 0
	global_load_lds_dwordx4 v[144:145], off
	s_waitcnt vmcnt(8)
	s_waitcnt lgkmcnt(0)
	s_barrier
	s_setprio 1
	s_waitcnt lgkmcnt(0)
	v_mfma_f32_16x16x32_bf16 v[126:129], v[140:143], v[190:193], v[126:129]
	v_mfma_f32_16x16x32_bf16 v[122:125], v[154:157], v[190:193], v[122:125]
	v_mfma_f32_16x16x32_bf16 v[110:113], v[140:143], v[198:201], v[110:113]
	v_mfma_f32_16x16x32_bf16 v[106:109], v[154:157], v[198:201], v[106:109]
	v_mfma_f32_16x16x32_bf16 v[94:97], v[140:143], v[206:209], v[94:97]
	v_mfma_f32_16x16x32_bf16 v[90:93], v[154:157], v[206:209], v[90:93]
	v_mfma_f32_16x16x32_bf16 v[78:81], v[140:143], v[214:217], v[78:81]
	v_mfma_f32_16x16x32_bf16 v[74:77], v[154:157], v[214:217], v[74:77]
	v_mfma_f32_16x16x32_bf16 v[126:129], v[150:153], v[194:197], v[126:129]
	v_mfma_f32_16x16x32_bf16 v[122:125], v[158:161], v[194:197], v[122:125]
	v_mfma_f32_16x16x32_bf16 v[110:113], v[150:153], v[202:205], v[110:113]
	v_mfma_f32_16x16x32_bf16 v[106:109], v[158:161], v[202:205], v[106:109]
	v_mfma_f32_16x16x32_bf16 v[94:97], v[150:153], v[210:213], v[94:97]
	v_mfma_f32_16x16x32_bf16 v[90:93], v[158:161], v[210:213], v[90:93]
	v_mfma_f32_16x16x32_bf16 v[78:81], v[150:153], v[218:221], v[78:81]
	v_mfma_f32_16x16x32_bf16 v[74:77], v[158:161], v[218:221], v[74:77]
	v_mfma_f32_16x16x32_bf16 v[118:121], v[174:177], v[190:193], v[118:121]
	v_mfma_f32_16x16x32_bf16 v[114:117], v[182:185], v[190:193], v[114:117]
	v_mfma_f32_16x16x32_bf16 v[102:105], v[174:177], v[198:201], v[102:105]
	v_mfma_f32_16x16x32_bf16 v[98:101], v[182:185], v[198:201], v[98:101]
	v_mfma_f32_16x16x32_bf16 v[86:89], v[174:177], v[206:209], v[86:89]
	v_mfma_f32_16x16x32_bf16 v[82:85], v[182:185], v[206:209], v[82:85]
	v_mfma_f32_16x16x32_bf16 v[70:73], v[174:177], v[214:217], v[70:73]
	v_mfma_f32_16x16x32_bf16 v[66:69], v[182:185], v[214:217], v[66:69]
	v_mfma_f32_16x16x32_bf16 v[118:121], v[178:181], v[194:197], v[118:121]
	v_mfma_f32_16x16x32_bf16 v[114:117], v[186:189], v[194:197], v[114:117]
	v_mfma_f32_16x16x32_bf16 v[102:105], v[178:181], v[202:205], v[102:105]
	v_mfma_f32_16x16x32_bf16 v[98:101], v[186:189], v[202:205], v[98:101]
	v_mfma_f32_16x16x32_bf16 v[86:89], v[178:181], v[210:213], v[86:89]
	v_mfma_f32_16x16x32_bf16 v[82:85], v[186:189], v[210:213], v[82:85]
	v_mfma_f32_16x16x32_bf16 v[70:73], v[178:181], v[218:221], v[70:73]
	v_mfma_f32_16x16x32_bf16 v[66:69], v[186:189], v[218:221], v[66:69]
	s_setprio 0
	s_barrier
	s_add_i32 s12, s64, s52
	v_lshl_add_u64 v[144:145], s[44:45], 0, v[0:1]
	s_mov_b32 m0, s12
	ds_read_b128 v[190:193], v149 offset:16384
	ds_read_b128 v[194:197], v149 offset:17408
	ds_read_b128 v[198:201], v149 offset:18432
	ds_read_b128 v[202:205], v149 offset:19456
	ds_read_b128 v[206:209], v149 offset:20480
	ds_read_b128 v[210:213], v149 offset:21504
	ds_read_b128 v[214:217], v149 offset:22528
	ds_read_b128 v[218:221], v149 offset:23552
	global_load_lds_dwordx4 v[144:145], off
	s_add_i32 m0, s12, 0x2000
	s_add_u32 s12, s44, 0x56000
	v_lshl_add_u64 v[222:223], s[44:45], 0, v[134:135]
	s_addc_u32 s13, s45, 0
	s_add_i32 s64, s65, s52
	global_load_lds_dwordx4 v[222:223], off
	v_lshl_add_u64 v[224:225], s[12:13], 0, v[0:1]
	s_mov_b32 m0, s64
	v_lshl_add_u64 v[226:227], s[46:47], 0, v[132:133]
	global_load_lds_dwordx4 v[224:225], off
	v_lshl_add_u64 v[224:225], s[12:13], 0, v[134:135]
	s_add_i32 m0, s64, 0x2000
	s_nop 0
	global_load_lds_dwordx4 v[224:225], off
	v_lshl_add_u64 v[224:225], s[46:47], 0, v[130:131]
	s_mov_b32 m0, s53
	s_nop 0
	global_load_lds_dwordx4 v[224:225], off
	s_mov_b32 m0, s54
	s_nop 0
	global_load_lds_dwordx4 v[226:227], off
	s_waitcnt vmcnt(8)
	s_waitcnt lgkmcnt(0)
	s_barrier
; #define PG8_STAGE(bufoff, gbase, voff) do { _Pragma("unroll") for (int _i = 0; _i < 2; ++_i) \
;         __builtin_amdgcn_global_load_lds((const __attribute__((address_space(1))) unsigned*)((const char*)(gbase) + (voff)[_i]), (LAS unsigned*)(lds + (bufoff) + ldsw + _i * 8192), 16, 0, 0); } while (0)
; #define PG8_LDA(dst, b, h) do { _Pragma("unroll") for (int m = 0; m < 4; ++m) _Pragma("unroll") for (int k = 0; k < 2; ++k) dst[m][k] = *(const LAS bf16x8*)(lds + PG8_SA(b, h) + aoff + m * 2048 + k * 1024); } while (0)
; #define PG8_LDB(dst, b, h) do { _Pragma("unroll") for (int n = 0; n < 2; ++n) _Pragma("unroll") for (int k = 0; k < 2; ++k) dst[n][k] = *(const LAS bf16x8*)(lds + PG8_SB(b, h) + boff + n * 2048 + k * 1024); } while (0)
; #define PG8_MMA(ai, bj, At, Bt) do { __builtin_amdgcn_s_setprio(1); _Pragma("unroll") for (int m = 0; m < 4; ++m) _Pragma("unroll") for (int n = 0; n < 2; ++n) _Pragma("unroll") for (int k = 0; k < 2; ++k) \
;         acc[ai][bj][m][n] = __builtin_amdgcn_mfma_f32_16x16x32_bf16(Bt[n][k], At[m][k], acc[ai][bj][m][n], 0, 0, 0); __builtin_amdgcn_s_setprio(0); } while (0)
; #define PG8_WAIT_V(n) asm volatile("s_waitcnt vmcnt(" #n ")" ::: "memory")
; #define PG8_WAIT_L(n) asm volatile("s_waitcnt lgkmcnt(" #n ")" ::: "memory")
; #define PG8_BAR __builtin_amdgcn_s_barrier()
; #define PG8_SCHED __builtin_amdgcn_sched_barrier(0)
; template <class Epi, class SchedT, bool ALIGN_EPI, bool SP2>
; __device__ __forceinline__ void gemm_phase(LAS unsigned char* lds, const int ldk, const int nt, const SchedT& S, const Epi& E) {
;     ...
;             PG8_WAIT_V(8); PG8_WAIT_L(0); PG8_BAR; PG8_MMA(1, 0, At, B0); PG8_MMA(1, 1, At, B1); PG8_BAR; PG8_SCHED;
;             PG8_LDB(B0, 1, 0); PG8_LDB(B1, 1, 1); PG8_SCHED; PG8_LDA(At, 1, 0); PG8_STAGE(PG8_SA(0, 1), a2 + hstep, voffA);
;             PG8_WAIT_V(8); PG8_WAIT_L(0); PG8_BAR; PG8_MMA(0, 0, At, B0); PG8_MMA(0, 1, At, B1); PG8_BAR; PG8_SCHED;
	s_setprio 1
	s_waitcnt lgkmcnt(0)
	v_mfma_f32_16x16x32_bf16 v[62:65], v[140:143], v[190:193], v[62:65]
	v_mfma_f32_16x16x32_bf16 v[58:61], v[154:157], v[190:193], v[58:61]
	v_mfma_f32_16x16x32_bf16 v[46:49], v[140:143], v[198:201], v[46:49]
	v_mfma_f32_16x16x32_bf16 v[42:45], v[154:157], v[198:201], v[42:45]
	v_mfma_f32_16x16x32_bf16 v[30:33], v[140:143], v[206:209], v[30:33]
	v_mfma_f32_16x16x32_bf16 v[26:29], v[154:157], v[206:209], v[26:29]
	v_mfma_f32_16x16x32_bf16 v[14:17], v[140:143], v[214:217], v[14:17]
	v_mfma_f32_16x16x32_bf16 v[10:13], v[154:157], v[214:217], v[10:13]
	v_mfma_f32_16x16x32_bf16 v[62:65], v[150:153], v[194:197], v[62:65]
	v_mfma_f32_16x16x32_bf16 v[58:61], v[158:161], v[194:197], v[58:61]
	v_mfma_f32_16x16x32_bf16 v[46:49], v[150:153], v[202:205], v[46:49]
	v_mfma_f32_16x16x32_bf16 v[42:45], v[158:161], v[202:205], v[42:45]
	v_mfma_f32_16x16x32_bf16 v[30:33], v[150:153], v[210:213], v[30:33]
	v_mfma_f32_16x16x32_bf16 v[26:29], v[158:161], v[210:213], v[26:29]
	v_mfma_f32_16x16x32_bf16 v[14:17], v[150:153], v[218:221], v[14:17]
	v_mfma_f32_16x16x32_bf16 v[10:13], v[158:161], v[218:221], v[10:13]
	v_mfma_f32_16x16x32_bf16 v[54:57], v[174:177], v[190:193], v[54:57]
	v_mfma_f32_16x16x32_bf16 v[50:53], v[182:185], v[190:193], v[50:53]
	v_mfma_f32_16x16x32_bf16 v[38:41], v[174:177], v[198:201], v[38:41]
	v_mfma_f32_16x16x32_bf16 v[34:37], v[182:185], v[198:201], v[34:37]
	v_mfma_f32_16x16x32_bf16 v[22:25], v[174:177], v[206:209], v[22:25]
	v_mfma_f32_16x16x32_bf16 v[18:21], v[182:185], v[206:209], v[18:21]
	v_mfma_f32_16x16x32_bf16 v[6:9], v[174:177], v[214:217], v[6:9]
	v_mfma_f32_16x16x32_bf16 v[2:5], v[182:185], v[214:217], v[2:5]
	v_mfma_f32_16x16x32_bf16 v[54:57], v[178:181], v[194:197], v[54:57]
	v_mfma_f32_16x16x32_bf16 v[50:53], v[186:189], v[194:197], v[50:53]
	v_mfma_f32_16x16x32_bf16 v[38:41], v[178:181], v[202:205], v[38:41]
	v_mfma_f32_16x16x32_bf16 v[34:37], v[186:189], v[202:205], v[34:37]
	v_mfma_f32_16x16x32_bf16 v[22:25], v[178:181], v[210:213], v[22:25]
	v_mfma_f32_16x16x32_bf16 v[18:21], v[186:189], v[210:213], v[18:21]
	v_mfma_f32_16x16x32_bf16 v[6:9], v[178:181], v[218:221], v[6:9]
	v_mfma_f32_16x16x32_bf16 v[2:5], v[186:189], v[218:221], v[2:5]
	s_setprio 0
	s_barrier
	s_add_i32 s64, 0, 0x18000
	s_add_i32 s65, 0, 0x1c000
	v_add_u32_e32 v158, s64, v147
	v_add_u32_e32 v186, s65, v147
	ds_read_b128 v[140:143], v158
	ds_read_b128 v[150:153], v158 offset:1024
	ds_read_b128 v[154:157], v158 offset:2048
	ds_read_b128 v[158:161], v158 offset:3072
	ds_read_b128 v[174:177], v186
	ds_read_b128 v[178:181], v186 offset:1024
	ds_read_b128 v[182:185], v186 offset:2048
	ds_read_b128 v[186:189], v186 offset:3072
	s_add_u32 s12, s46, 0x158000
	s_addc_u32 s13, s47, 0
	s_mov_b32 m0, s55
	v_lshl_add_u64 v[228:229], s[12:13], 0, v[130:131]
	ds_read_b128 v[190:193], v149 offset:32768
	ds_read_b128 v[194:197], v149 offset:33792
	ds_read_b128 v[198:201], v149 offset:34816
	ds_read_b128 v[202:205], v149 offset:35840
	ds_read_b128 v[206:209], v149 offset:36864
	ds_read_b128 v[210:213], v149 offset:37888
	ds_read_b128 v[214:217], v149 offset:38912
	ds_read_b128 v[218:221], v149 offset:39936
	global_load_lds_dwordx4 v[228:229], off
	v_lshl_add_u64 v[228:229], s[12:13], 0, v[132:133]
	s_mov_b32 m0, s56
	s_nop 0
	global_load_lds_dwordx4 v[228:229], off
	s_waitcnt vmcnt(8)
	s_waitcnt lgkmcnt(0)
	s_barrier
	s_setprio 1
	s_waitcnt lgkmcnt(0)
	v_mfma_f32_16x16x32_bf16 v[126:129], v[140:143], v[190:193], v[126:129]
	v_mfma_f32_16x16x32_bf16 v[122:125], v[154:157], v[190:193], v[122:125]
	v_mfma_f32_16x16x32_bf16 v[110:113], v[140:143], v[198:201], v[110:113]
	v_mfma_f32_16x16x32_bf16 v[106:109], v[154:157], v[198:201], v[106:109]
	v_mfma_f32_16x16x32_bf16 v[94:97], v[140:143], v[206:209], v[94:97]
	v_mfma_f32_16x16x32_bf16 v[90:93], v[154:157], v[206:209], v[90:93]
	v_mfma_f32_16x16x32_bf16 v[78:81], v[140:143], v[214:217], v[78:81]
	v_mfma_f32_16x16x32_bf16 v[74:77], v[154:157], v[214:217], v[74:77]
	v_mfma_f32_16x16x32_bf16 v[126:129], v[150:153], v[194:197], v[126:129]
	v_mfma_f32_16x16x32_bf16 v[122:125], v[158:161], v[194:197], v[122:125]
	v_mfma_f32_16x16x32_bf16 v[110:113], v[150:153], v[202:205], v[110:113]
	v_mfma_f32_16x16x32_bf16 v[106:109], v[158:161], v[202:205], v[106:109]
	v_mfma_f32_16x16x32_bf16 v[94:97], v[150:153], v[210:213], v[94:97]
	v_mfma_f32_16x16x32_bf16 v[90:93], v[158:161], v[210:213], v[90:93]
	v_mfma_f32_16x16x32_bf16 v[78:81], v[150:153], v[218:221], v[78:81]
	v_mfma_f32_16x16x32_bf16 v[74:77], v[158:161], v[218:221], v[74:77]
	v_mfma_f32_16x16x32_bf16 v[118:121], v[174:177], v[190:193], v[118:121]
	v_mfma_f32_16x16x32_bf16 v[114:117], v[182:185], v[190:193], v[114:117]
	v_mfma_f32_16x16x32_bf16 v[102:105], v[174:177], v[198:201], v[102:105]
	v_mfma_f32_16x16x32_bf16 v[98:101], v[182:185], v[198:201], v[98:101]
	v_mfma_f32_16x16x32_bf16 v[86:89], v[174:177], v[206:209], v[86:89]
	v_mfma_f32_16x16x32_bf16 v[82:85], v[182:185], v[206:209], v[82:85]
	v_mfma_f32_16x16x32_bf16 v[70:73], v[174:177], v[214:217], v[70:73]
	v_mfma_f32_16x16x32_bf16 v[66:69], v[182:185], v[214:217], v[66:69]
	v_mfma_f32_16x16x32_bf16 v[118:121], v[178:181], v[194:197], v[118:121]
	v_mfma_f32_16x16x32_bf16 v[114:117], v[186:189], v[194:197], v[114:117]
	v_mfma_f32_16x16x32_bf16 v[102:105], v[178:181], v[202:205], v[102:105]
	v_mfma_f32_16x16x32_bf16 v[98:101], v[186:189], v[202:205], v[98:101]
	v_mfma_f32_16x16x32_bf16 v[86:89], v[178:181], v[210:213], v[86:89]
	v_mfma_f32_16x16x32_bf16 v[82:85], v[186:189], v[210:213], v[82:85]
	v_mfma_f32_16x16x32_bf16 v[70:73], v[178:181], v[218:221], v[70:73]
	v_mfma_f32_16x16x32_bf16 v[66:69], v[186:189], v[218:221], v[66:69]
	s_setprio 0
	s_barrier
; #define PG8_STAGE(bufoff, gbase, voff) do { _Pragma("unroll") for (int _i = 0; _i < 2; ++_i) \
;         __builtin_amdgcn_global_load_lds((const __attribute__((address_space(1))) unsigned*)((const char*)(gbase) + (voff)[_i]), (LAS unsigned*)(lds + (bufoff) + ldsw + _i * 8192), 16, 0, 0); } while (0)
; #define PG8_LDA(dst, b, h) do { _Pragma("unroll") for (int m = 0; m < 4; ++m) _Pragma("unroll") for (int k = 0; k < 2; ++k) dst[m][k] = *(const LAS bf16x8*)(lds + PG8_SA(b, h) + aoff + m * 2048 + k * 1024); } while (0)
; #define PG8_MMA(ai, bj, At, Bt) do { __builtin_amdgcn_s_setprio(1); _Pragma("unroll") for (int m = 0; m < 4; ++m) _Pragma("unroll") for (int n = 0; n < 2; ++n) _Pragma("unroll") for (int k = 0; k < 2; ++k) \
;         acc[ai][bj][m][n] = __builtin_amdgcn_mfma_f32_16x16x32_bf16(Bt[n][k], At[m][k], acc[ai][bj][m][n], 0, 0, 0); __builtin_amdgcn_s_setprio(0); } while (0)
; #define PG8_WAIT_V(n) asm volatile("s_waitcnt vmcnt(" #n ")" ::: "memory")
; #define PG8_WAIT_L(n) asm volatile("s_waitcnt lgkmcnt(" #n ")" ::: "memory")
; #define PG8_BAR __builtin_amdgcn_s_barrier()
; #define PG8_SCHED __builtin_amdgcn_sched_barrier(0)
; template <class Epi, class SchedT, bool ALIGN_EPI, bool SP2>
; __device__ __forceinline__ void gemm_phase(LAS unsigned char* lds, const int ldk, const int nt, const SchedT& S, const Epi& E) {
;     ...
;             PG8_LDA(At, 1, 1); PG8_STAGE(PG8_SB(1, 0), b3, voffB); PG8_STAGE(PG8_SB(1, 1), b3 + hstepB, voffB); PG8_STAGE(PG8_SA(1, 0), a3, voffA);
;             PG8_WAIT_V(8); PG8_WAIT_L(0); PG8_BAR; PG8_MMA(1, 0, At, B0); PG8_MMA(1, 1, At, B1); PG8_BAR; PG8_SCHED;
;     ...
;         if constexpr (ALIGN_EPI) { if (wr == 0) PG8_BAR; }
;     __device__ __forceinline__ void operator()(f32x4 (&acc)[2][2][4][2], const Unit& u, int wr, int wc, int fr, int fq) const {
;     ...
;                 const int row = row0 + ai * HALF + m * 16; float sq = 0.f;
; #pragma unroll
;                 for (int bj = 0; bj < 2; ++bj) {
;                     const size_t off = (size_t)row * D + col0 + bj * 32;
;                     const u32x4 xw = *(const u32x4*)(xin + off);
	s_add_i32 s12, s64, s52
	v_lshl_add_u64 v[144:145], v[144:145], 0, s[24:25]
	s_mov_b32 m0, s12
	ds_read_b128 v[190:193], v149 offset:49152
	ds_read_b128 v[194:197], v149 offset:50176
	ds_read_b128 v[198:201], v149 offset:51200
	ds_read_b128 v[202:205], v149 offset:52224
	ds_read_b128 v[206:209], v149 offset:53248
	ds_read_b128 v[210:213], v149 offset:54272
	ds_read_b128 v[214:217], v149 offset:55296
	ds_read_b128 v[218:221], v149 offset:56320
	global_load_lds_dwordx4 v[144:145], off
	s_add_i32 m0, s12, 0x2000
	s_add_u32 s12, s44, 0x56080
	v_lshl_add_u64 v[144:145], v[222:223], 0, s[24:25]
	s_addc_u32 s13, s45, 0
	s_add_i32 s44, s65, s52
	global_load_lds_dwordx4 v[144:145], off
	v_lshl_add_u64 v[144:145], s[12:13], 0, v[0:1]
	s_mov_b32 m0, s44
	s_nop 0
	global_load_lds_dwordx4 v[144:145], off
	v_lshl_add_u64 v[144:145], s[12:13], 0, v[134:135]
	s_add_i32 m0, s44, 0x2000
	s_nop 0
	global_load_lds_dwordx4 v[144:145], off
	v_lshl_add_u64 v[144:145], v[224:225], 0, s[24:25]
	s_mov_b32 m0, s58
	s_nop 0
	global_load_lds_dwordx4 v[144:145], off
	v_lshl_add_u64 v[144:145], v[226:227], 0, s[24:25]
	s_mov_b32 m0, s59
	s_nop 0
	global_load_lds_dwordx4 v[144:145], off
	s_waitcnt vmcnt(8)
	s_waitcnt lgkmcnt(0)
	s_barrier
	s_setprio 1
	s_waitcnt lgkmcnt(0)
	v_mfma_f32_16x16x32_bf16 v[62:65], v[140:143], v[190:193], v[62:65]
	v_mfma_f32_16x16x32_bf16 v[58:61], v[154:157], v[190:193], v[58:61]
	v_mfma_f32_16x16x32_bf16 v[46:49], v[140:143], v[198:201], v[46:49]
	v_mfma_f32_16x16x32_bf16 v[42:45], v[154:157], v[198:201], v[42:45]
	v_mfma_f32_16x16x32_bf16 v[30:33], v[140:143], v[206:209], v[30:33]
	v_mfma_f32_16x16x32_bf16 v[26:29], v[154:157], v[206:209], v[26:29]
	v_mfma_f32_16x16x32_bf16 v[14:17], v[140:143], v[214:217], v[14:17]
	v_mfma_f32_16x16x32_bf16 v[10:13], v[154:157], v[214:217], v[10:13]
	v_mfma_f32_16x16x32_bf16 v[62:65], v[150:153], v[194:197], v[62:65]
	v_mfma_f32_16x16x32_bf16 v[58:61], v[158:161], v[194:197], v[58:61]
	v_mfma_f32_16x16x32_bf16 v[46:49], v[150:153], v[202:205], v[46:49]
	v_mfma_f32_16x16x32_bf16 v[42:45], v[158:161], v[202:205], v[42:45]
	v_mfma_f32_16x16x32_bf16 v[30:33], v[150:153], v[210:213], v[30:33]
	v_mfma_f32_16x16x32_bf16 v[26:29], v[158:161], v[210:213], v[26:29]
	v_mfma_f32_16x16x32_bf16 v[14:17], v[150:153], v[218:221], v[14:17]
	v_mfma_f32_16x16x32_bf16 v[10:13], v[158:161], v[218:221], v[10:13]
	v_mfma_f32_16x16x32_bf16 v[54:57], v[174:177], v[190:193], v[54:57]
	v_mfma_f32_16x16x32_bf16 v[50:53], v[182:185], v[190:193], v[50:53]
	v_mfma_f32_16x16x32_bf16 v[38:41], v[174:177], v[198:201], v[38:41]
	v_mfma_f32_16x16x32_bf16 v[34:37], v[182:185], v[198:201], v[34:37]
	v_mfma_f32_16x16x32_bf16 v[22:25], v[174:177], v[206:209], v[22:25]
	v_mfma_f32_16x16x32_bf16 v[18:21], v[182:185], v[206:209], v[18:21]
	v_mfma_f32_16x16x32_bf16 v[6:9], v[174:177], v[214:217], v[6:9]
	v_mfma_f32_16x16x32_bf16 v[2:5], v[182:185], v[214:217], v[2:5]
	v_mfma_f32_16x16x32_bf16 v[54:57], v[178:181], v[194:197], v[54:57]
	v_mfma_f32_16x16x32_bf16 v[50:53], v[186:189], v[194:197], v[50:53]
	v_mfma_f32_16x16x32_bf16 v[38:41], v[178:181], v[202:205], v[38:41]
	v_mfma_f32_16x16x32_bf16 v[34:37], v[186:189], v[202:205], v[34:37]
	v_mfma_f32_16x16x32_bf16 v[22:25], v[178:181], v[210:213], v[22:25]
	v_mfma_f32_16x16x32_bf16 v[18:21], v[186:189], v[210:213], v[18:21]
	v_mfma_f32_16x16x32_bf16 v[6:9], v[178:181], v[218:221], v[6:9]
	v_mfma_f32_16x16x32_bf16 v[2:5], v[186:189], v[218:221], v[2:5]
	s_setprio 0
	s_barrier
	s_add_i32 s83, s83, 2
	s_add_u32 s81, s81, 0x100
	s_addc_u32 s82, s82, 0
	s_cmpk_gt_u32 s83, 0x53
	s_mov_b64 s[12:13], s[16:17]
	s_cbranch_scc0 .LBB0_948
	v_lshl_add_u32 v142, s63, 8, v146
	v_lshl_or_b32 v140, s22, 8, v148
	v_lshlrev_b32_e32 v141, 12, v142
	v_lshl_add_u32 v150, v140, 1, v141
	v_add_u32_e32 v151, 0x10000, v150
	v_add_u32_e32 v152, 0x20000, v150
	v_add_u32_e32 v153, 0x30000, v150
	v_add_u32_e32 v154, 0x80000, v150
	v_add_u32_e32 v155, 0x90000, v150
	v_add_u32_e32 v156, 0xa0000, v150
	v_add_u32_e32 v157, 0xb0000, v150
	global_load_dwordx4 v[174:177], v150, s[20:21]
	global_load_dwordx4 v[178:181], v150, s[20:21] offset:64
	global_load_dwordx4 v[182:185], v151, s[20:21]
	global_load_dwordx4 v[186:189], v151, s[20:21] offset:64
	global_load_dwordx4 v[190:193], v152, s[20:21]
	global_load_dwordx4 v[194:197], v152, s[20:21] offset:64
	global_load_dwordx4 v[198:201], v153, s[20:21]
	global_load_dwordx4 v[202:205], v153, s[20:21] offset:64
	global_load_dwordx4 v[206:209], v154, s[20:21]
	global_load_dwordx4 v[210:213], v154, s[20:21] offset:64
	global_load_dwordx4 v[214:217], v155, s[20:21]
	global_load_dwordx4 v[218:221], v155, s[20:21] offset:64
	global_load_dwordx4 v[222:225], v156, s[20:21]
	global_load_dwordx4 v[226:229], v156, s[20:21] offset:64
	global_load_dwordx4 v[230:233], v157, s[20:21]
	global_load_dwordx4 v[234:237], v157, s[20:21] offset:64
	s_lshl_b32 s44, s22, 4
	s_lshl_b32 s45, s57, 2
	s_add_i32 s44, s44, s45
	v_lshl_add_u32 v158, v142, 7, s44
	v_add_u32_e32 v159, 0x1000, v158
	v_add_u32_e32 v160, 0x4000, v158
	v_add_u32_e32 v161, 0x5000, v158
	v_xor_b32_e32 v239, 16, v241
	v_xor_b32_e32 v252, 32, v241
	v_lshlrev_b32_e32 v239, 2, v239
	v_lshlrev_b32_e32 v252, 2, v252
	s_and_b64 vcc, exec, s[40:41]
	s_cbranch_vccz .LBB0_951
	s_barrier
	s_setprio 3

; #define PG8_WAIT_V(n) asm volatile("s_waitcnt vmcnt(" #n ")" ::: "memory")
; #define PG8_BAR __builtin_amdgcn_s_barrier()
; template <class Epi, class SchedT, bool ALIGN_EPI, bool SP2>
; __device__ __forceinline__ void gemm_phase(LAS unsigned char* lds, const int ldk, const int nt, const SchedT& S, const Epi& E) {
;     ...
;     PG8_WAIT_V(0);
;     if constexpr (!ALIGN_EPI) { if (wr == 0) PG8_BAR; }
;     PG8_BAR;
.LBB0_970:
	s_setprio 0
	s_waitcnt vmcnt(0)
	v_readlane_b32 s60, v163, 31
	v_readlane_b32 s61, v163, 32
	v_readlane_b32 s52, v163, 34
	v_readlane_b32 s53, v163, 35
	s_movk_i32 s54, 0x2000
	s_movk_i32 s55, 0x4000
	s_movk_i32 s56, 0x6000
	s_mov_b32 s57, 0x18000
	s_mov_b32 s58, 0x8000
	s_mov_b32 s50, 0x30000
	s_barrier
